# conversion tiles: later row groups take the prefetched registers instead of re-loading (3 fewer round trips per tile)
# baseline (speedup 1.0000x reference)
; template <bool MAP = false>
; DI void conv_tile(const float* __restrict__ src, int N, int K, bfu* __restrict__ dst, const float* __restrict__ g,
;                   int tk, int tn, char* smem, int ldk = -1) {
;     ...
;   for (int j = 0; j < 4; ++j) {
;     int k = (tid >> 4) + 16 * j, n4 = (tid & 15) * 4;
;     int gn = tn * 64 + n4, gk = tk * 64 + k;
;     float4 v = make_float4(0.f, 0.f, 0.f, 0.f);
;     const int og = MAP ? in_colmap(gn) : (gn < N ? gn : -1);
;     if (og >= 0) v = *(const float4*)(src + (size_t)gk * N + og);
;     float gg = g ? g[gk] : 1.f;
;     T[k * 65 + n4 + 0] = v.x * gg; T[k * 65 + n4 + 1] = v.y * gg; T[k * 65 + n4 + 2] = v.z * gg; T[k * 65 + n4 + 3] = v.w * gg;
;   }
.LBB0_49:
	s_movk_i32 s12, 0x104
	v_lshlrev_b32_e32 v9, 2, v14
	s_waitcnt vmcnt(0)
	v_pk_mul_f32 v[0:1], v[0:1], v[12:13] op_sel_hi:[1,0]
	v_mul_lo_u32 v13, v13, s12
	v_add_u32_e32 v9, v9, v13
	ds_write2_b32 v9, v0, v1 offset1:1
	v_pk_mul_f32 v[0:1], v[2:3], v[12:13] op_sel_hi:[1,0]
	ds_write2_b32 v9, v0, v1 offset0:2 offset1:3
	v_add_u32_e32 v0, 16, v8
	v_ashrrev_i32_e32 v1, 31, v0
	v_lshlrev_b64 v[0:1], 11, v[0:1]
	v_lshl_add_u64 v[0:1], v[6:7], 0, v[0:1]
	v_mov_b32_e32 v0, v240
	v_mov_b32_e32 v1, v241
	v_mov_b32_e32 v2, v242
	v_mov_b32_e32 v3, v243
	s_and_b64 vcc, exec, s[2:3]
	s_cbranch_vccnz .LBB0_51
	global_load_dword v10, v[4:5], off offset:64
.LBB0_51:
	s_waitcnt vmcnt(0)
	v_pk_mul_f32 v[0:1], v[0:1], v[10:11] op_sel_hi:[1,0]
	v_add_u32_e32 v12, 0x1040, v9
	ds_write2_b32 v12, v0, v1 offset1:1
	v_pk_mul_f32 v[0:1], v[2:3], v[10:11] op_sel_hi:[1,0]
	v_add_u32_e32 v2, 0x1048, v9
	ds_write2_b32 v2, v0, v1 offset1:1
	v_add_u32_e32 v0, 32, v8
	v_ashrrev_i32_e32 v1, 31, v0
	v_lshlrev_b64 v[0:1], 11, v[0:1]
	v_lshl_add_u64 v[0:1], v[6:7], 0, v[0:1]
	v_mov_b32_e32 v0, v244
	v_mov_b32_e32 v1, v245
	v_mov_b32_e32 v2, v246
	v_mov_b32_e32 v3, v247
	v_mov_b32_e32 v10, 1.0
	s_and_b64 vcc, exec, s[2:3]
	v_mov_b32_e32 v12, 1.0
	s_cbranch_vccnz .LBB0_53
	global_load_dword v12, v[4:5], off offset:128
.LBB0_53:
	s_waitcnt vmcnt(0)
	v_pk_mul_f32 v[0:1], v[0:1], v[12:13] op_sel_hi:[1,0]
	v_add_u32_e32 v13, 0x2080, v9
	ds_write2_b32 v13, v0, v1 offset1:1
	v_pk_mul_f32 v[0:1], v[2:3], v[12:13] op_sel_hi:[1,0]
	v_add_u32_e32 v2, 0x2088, v9
	ds_write2_b32 v2, v0, v1 offset1:1
	v_add_u32_e32 v0, 48, v8
	v_ashrrev_i32_e32 v1, 31, v0
	v_lshlrev_b64 v[0:1], 11, v[0:1]
	v_lshl_add_u64 v[0:1], v[6:7], 0, v[0:1]
	v_mov_b32_e32 v0, v248
	v_mov_b32_e32 v1, v249
	v_mov_b32_e32 v2, v250
	v_mov_b32_e32 v3, v251
	s_and_b64 vcc, exec, s[2:3]
	s_cbranch_vccnz .LBB0_55
	global_load_dword v10, v[4:5], off offset:192

; template <bool MAP = false>
; DI void conv_tile(const float* __restrict__ src, int N, int K, bfu* __restrict__ dst, const float* __restrict__ g,
;                   int tk, int tn, char* smem, int ldk = -1) {
;     ...
;   for (int j = 0; j < 4; ++j) {
;     int k = (tid >> 4) + 16 * j, n4 = (tid & 15) * 4;
;     int gn = tn * 64 + n4, gk = tk * 64 + k;
;     float4 v = make_float4(0.f, 0.f, 0.f, 0.f);
;     const int og = MAP ? in_colmap(gn) : (gn < N ? gn : -1);
;     if (og >= 0) v = *(const float4*)(src + (size_t)gk * N + og);
;     float gg = g ? g[gk] : 1.f;
;     T[k * 65 + n4 + 0] = v.x * gg; T[k * 65 + n4 + 1] = v.y * gg; T[k * 65 + n4 + 2] = v.z * gg; T[k * 65 + n4 + 3] = v.w * gg;
;   }
.LBB0_74:
	s_movk_i32 s12, 0x104
	v_lshlrev_b32_e32 v5, 2, v5
	v_mul_lo_u32 v7, v4, s12
	s_waitcnt vmcnt(0)
	v_pk_mul_f32 v[0:1], v[0:1], v[8:9] op_sel_hi:[1,0]
	v_add_u32_e32 v7, v5, v7
	ds_write2_b32 v7, v0, v1 offset1:1
	v_pk_mul_f32 v[0:1], v[2:3], v[8:9] op_sel_hi:[1,0]
	ds_write2_b32 v7, v0, v1 offset0:2 offset1:3
	v_mov_b32_e32 v0, 0
	v_mov_b32_e32 v1, 0
	v_mov_b32_e32 v2, 0
	v_mov_b32_e32 v3, 0
	s_and_saveexec_b64 vcc, s[2:3]
	s_cbranch_execz .LBB0_76
	v_add_u32_e32 v2, 16, v6
	v_mov_b64_e32 v[0:1], s[92:93]
	s_movk_i32 s12, 0x6ac0
	v_mad_i64_i32 v[0:1], s[28:29], v2, s12, v[0:1]
	v_lshl_add_u64 v[0:1], v[188:189], 2, v[0:1]
	v_mov_b32_e32 v0, v240
	v_mov_b32_e32 v1, v241
	v_mov_b32_e32 v2, v242
	v_mov_b32_e32 v3, v243

; template <bool MAP = false>
; DI void conv_tile(const float* __restrict__ src, int N, int K, bfu* __restrict__ dst, const float* __restrict__ g,
;                   int tk, int tn, char* smem, int ldk = -1) {
;     ...
;   for (int j = 0; j < 4; ++j) {
;     int k = (tid >> 4) + 16 * j, n4 = (tid & 15) * 4;
;     int gn = tn * 64 + n4, gk = tk * 64 + k;
;     float4 v = make_float4(0.f, 0.f, 0.f, 0.f);
;     const int og = MAP ? in_colmap(gn) : (gn < N ? gn : -1);
;     if (og >= 0) v = *(const float4*)(src + (size_t)gk * N + og);
;     float gg = g ? g[gk] : 1.f;
;     T[k * 65 + n4 + 0] = v.x * gg; T[k * 65 + n4 + 1] = v.y * gg; T[k * 65 + n4 + 2] = v.z * gg; T[k * 65 + n4 + 3] = v.w * gg;
;   }
.LBB0_79:
	s_waitcnt vmcnt(0)
	v_pk_mul_f32 v[0:1], v[0:1], v[8:9] op_sel_hi:[1,0]
	v_add_u32_e32 v10, 0x1040, v7
	ds_write2_b32 v10, v0, v1 offset1:1
	v_pk_mul_f32 v[0:1], v[2:3], v[8:9] op_sel_hi:[1,0]
	v_add_u32_e32 v2, 0x1048, v7
	ds_write2_b32 v2, v0, v1 offset1:1
	v_mov_b32_e32 v0, 0
	v_mov_b32_e32 v1, 0
	v_mov_b32_e32 v2, 0
	v_mov_b32_e32 v3, 0
	s_and_saveexec_b64 vcc, s[2:3]
	s_cbranch_execz .LBB0_81
	v_add_u32_e32 v2, 32, v6
	v_mov_b64_e32 v[0:1], s[92:93]
	s_movk_i32 s12, 0x6ac0
	v_mad_i64_i32 v[0:1], s[28:29], v2, s12, v[0:1]
	v_lshl_add_u64 v[0:1], v[188:189], 2, v[0:1]
	v_mov_b32_e32 v0, v244
	v_mov_b32_e32 v1, v245
	v_mov_b32_e32 v2, v246
	v_mov_b32_e32 v3, v247

; template <bool MAP = false>
; DI void conv_tile(const float* __restrict__ src, int N, int K, bfu* __restrict__ dst, const float* __restrict__ g,
;                   int tk, int tn, char* smem, int ldk = -1) {
;     ...
;   for (int j = 0; j < 4; ++j) {
;     int k = (tid >> 4) + 16 * j, n4 = (tid & 15) * 4;
;     int gn = tn * 64 + n4, gk = tk * 64 + k;
;     float4 v = make_float4(0.f, 0.f, 0.f, 0.f);
;     const int og = MAP ? in_colmap(gn) : (gn < N ? gn : -1);
;     if (og >= 0) v = *(const float4*)(src + (size_t)gk * N + og);
;     float gg = g ? g[gk] : 1.f;
;     T[k * 65 + n4 + 0] = v.x * gg; T[k * 65 + n4 + 1] = v.y * gg; T[k * 65 + n4 + 2] = v.z * gg; T[k * 65 + n4 + 3] = v.w * gg;
;   }
.LBB0_84:
	s_waitcnt vmcnt(0)
	v_pk_mul_f32 v[0:1], v[0:1], v[8:9] op_sel_hi:[1,0]
	v_add_u32_e32 v10, 0x2080, v7
	ds_write2_b32 v10, v0, v1 offset1:1
	v_pk_mul_f32 v[0:1], v[2:3], v[8:9] op_sel_hi:[1,0]
	v_add_u32_e32 v2, 0x2088, v7
	ds_write2_b32 v2, v0, v1 offset1:1
	v_mov_b32_e32 v0, 0
	v_mov_b32_e32 v1, 0
	v_mov_b32_e32 v2, 0
	v_mov_b32_e32 v3, 0
	s_and_saveexec_b64 s[4:5], s[2:3]
	s_cbranch_execz .LBB0_86
	v_add_u32_e32 v2, 48, v6
	v_mov_b64_e32 v[0:1], s[92:93]
	s_movk_i32 s2, 0x6ac0
	v_mad_i64_i32 v[0:1], s[2:3], v2, s2, v[0:1]
	v_lshl_add_u64 v[0:1], v[188:189], 2, v[0:1]
	v_mov_b32_e32 v0, v248
	v_mov_b32_e32 v1, v249
	v_mov_b32_e32 v2, v250
	v_mov_b32_e32 v3, v251

; DI int TID() { int t = threadIdx.x; asm volatile("" : "+v"(t)); return t; }
; DI unsigned pk2(float a, float b) { f32x2_t v = {a, b}; bf16x2_t r_ = __builtin_convertvector(v, bf16x2_t); return __builtin_bit_cast(unsigned, r_); }
; template <bool MAP = false>
; DI void conv_tile(const float* __restrict__ src, int N, int K, bfu* __restrict__ dst, const float* __restrict__ g,
;                   int tk, int tn, char* smem, int ldk = -1) {
;     ...
;   float* T = (float*)smem;
;   const int tid = TID();
;   __syncthreads();
; #pragma unroll
;   for (int j = 0; j < 4; ++j) {
;     int k = (tid >> 4) + 16 * j, n4 = (tid & 15) * 4;
;     int gn = tn * 64 + n4, gk = tk * 64 + k;
;     float4 v = make_float4(0.f, 0.f, 0.f, 0.f);
;     const int og = MAP ? in_colmap(gn) : (gn < N ? gn : -1);
;     if (og >= 0) v = *(const float4*)(src + (size_t)gk * N + og);
;     float gg = g ? g[gk] : 1.f;
;     T[k * 65 + n4 + 0] = v.x * gg; T[k * 65 + n4 + 1] = v.y * gg; T[k * 65 + n4 + 2] = v.z * gg; T[k * 65 + n4 + 3] = v.w * gg;
;   }
;   __syncthreads();
; #pragma unroll
;   for (int j = 0; j < 2; ++j) {
;     int n = (tid >> 3) + 32 * j, kc = tid & 7;
;     float e[8];
; #pragma unroll
;     for (int q = 0; q < 8; ++q) e[q] = T[(kc * 8 + q) * 65 + n];
;     u32x4 o = {pk2(e[0], e[1]), pk2(e[2], e[3]), pk2(e[4], e[5]), pk2(e[6], e[7])};
;     *(u32x4*)(dst + (size_t)(tn * 64 + n) * LK + tk * 64 + kc * 8) = o;
;   }
.LBB0_162:
	s_andn2_b64 vcc, exec, s[2:3]
	s_cbranch_vccnz .LBB0_164
	v_mov_b32_e32 v8, v224
	s_lshl_b32 s3, s6, 2
	s_lshl_b32 s2, s6, 6
	v_lshlrev_b32_e32 v0, 2, v8
	s_and_b32 s3, s3, 0x3fc0
	v_ashrrev_i32_e32 v2, 4, v8
	v_and_b32_e32 v3, 60, v0
	s_and_b32 s2, s2, 0x3c0
	s_add_i32 s96, s3, 0xffffd400
	v_or_b32_e32 v0, s2, v3
	v_add_u32_e32 v6, s96, v2
	v_lshlrev_b32_e32 v188, 2, v0
	v_ashrrev_i32_e32 v7, 31, v6
	v_lshl_add_u64 v[4:5], s[64:65], 0, v[188:189]
	v_lshlrev_b64 v[0:1], 12, v[6:7]
	s_movk_i32 s3, 0x104
	v_lshl_add_u64 v[0:1], v[4:5], 0, v[0:1]
	v_mul_lo_u32 v2, v2, s3
	s_waitcnt vmcnt(63) expcnt(7) lgkmcnt(15)
	s_barrier
	v_lshl_add_u32 v7, v3, 2, v2
	v_add_u32_e32 v210, 16, v6
	v_ashrrev_i32_e32 v211, 31, v210
	v_lshlrev_b64 v[210:211], 12, v[210:211]
	v_lshl_add_u64 v[210:211], v[4:5], 0, v[210:211]
	global_load_dwordx4 v[240:243], v[210:211], off
	v_add_u32_e32 v210, 32, v6
	v_ashrrev_i32_e32 v211, 31, v210
	v_lshlrev_b64 v[210:211], 12, v[210:211]
	v_lshl_add_u64 v[210:211], v[4:5], 0, v[210:211]
	global_load_dwordx4 v[244:247], v[210:211], off
	v_add_u32_e32 v210, 48, v6
	v_ashrrev_i32_e32 v211, 31, v210
	v_lshlrev_b64 v[210:211], 12, v[210:211]
	v_lshl_add_u64 v[210:211], v[4:5], 0, v[210:211]
	global_load_dwordx4 v[248:251], v[210:211], off
	global_load_dwordx4 v[0:3], v[0:1], off
	v_add_u32_e32 v9, 0x1040, v7
	v_ashrrev_i32_e32 v22, 3, v8
	v_readlane_b32 s16, v253, 48
	s_lshl_b64 s[4:5], s[96:97], 1
	v_readlane_b32 s30, v253, 62
	v_readlane_b32 s31, v253, 63
	s_add_u32 s4, s30, s4
	s_addc_u32 s5, s31, s5
	v_readlane_b32 s17, v253, 49
	v_readlane_b32 s18, v253, 50
	v_readlane_b32 s19, v253, 51
	v_readlane_b32 s20, v253, 52
	v_readlane_b32 s21, v253, 53
	v_readlane_b32 s22, v253, 54
	v_readlane_b32 s23, v253, 55
	v_readlane_b32 s24, v253, 56
	v_readlane_b32 s25, v253, 57
	v_readlane_b32 s26, v253, 58
	v_readlane_b32 s27, v253, 59
	v_readlane_b32 s28, v253, 60
	v_readlane_b32 s29, v253, 61
	s_waitcnt vmcnt(0)
	ds_write2_b32 v7, v0, v1 offset1:1
	ds_write2_b32 v7, v2, v3 offset0:2 offset1:3
	v_add_u32_e32 v0, 16, v6
	v_ashrrev_i32_e32 v1, 31, v0
	v_lshlrev_b64 v[0:1], 12, v[0:1]
	v_lshl_add_u64 v[0:1], v[4:5], 0, v[0:1]
	v_mov_b32_e32 v0, v240
	v_mov_b32_e32 v1, v241
	v_mov_b32_e32 v2, v242
	v_mov_b32_e32 v3, v243
	s_waitcnt vmcnt(0)
	ds_write2_b32 v9, v0, v1 offset1:1
	v_add_u32_e32 v0, 0x1048, v7
	ds_write2_b32 v0, v2, v3 offset1:1
	v_add_u32_e32 v0, 32, v6
	v_ashrrev_i32_e32 v1, 31, v0
	v_lshlrev_b64 v[0:1], 12, v[0:1]
	v_lshl_add_u64 v[0:1], v[4:5], 0, v[0:1]
	v_mov_b32_e32 v0, v244
	v_mov_b32_e32 v1, v245
	v_mov_b32_e32 v2, v246
	v_mov_b32_e32 v3, v247
	v_add_u32_e32 v9, 0x2080, v7
	s_waitcnt vmcnt(0)
	ds_write2_b32 v9, v0, v1 offset1:1
	v_add_u32_e32 v0, 0x2088, v7
	ds_write2_b32 v0, v2, v3 offset1:1
	v_add_u32_e32 v0, 48, v6
	v_ashrrev_i32_e32 v1, 31, v0
	v_lshlrev_b64 v[0:1], 12, v[0:1]
	v_lshl_add_u64 v[0:1], v[4:5], 0, v[0:1]
	v_mov_b32_e32 v0, v248
	v_mov_b32_e32 v1, v249
	v_mov_b32_e32 v2, v250
	v_mov_b32_e32 v3, v251
	v_add_u32_e32 v4, 0x30c0, v7
	s_waitcnt vmcnt(0)
	ds_write2_b32 v4, v0, v1 offset1:1
	v_add_u32_e32 v0, 0x30c8, v7
	ds_write2_b32 v0, v2, v3 offset1:1
	v_lshlrev_b32_e32 v0, 3, v8
	v_and_b32_e32 v2, 56, v0
	v_lshlrev_b32_e32 v188, 1, v2
	v_mul_u32_u24_e32 v2, 0x104, v2
	v_lshl_add_u32 v2, v22, 2, v2
	s_waitcnt lgkmcnt(0)
	s_barrier
	ds_read2_b32 v[6:7], v2 offset1:32
	ds_read2_b32 v[8:9], v2 offset0:65 offset1:97
	ds_read2_b32 v[10:11], v2 offset0:130 offset1:162
	ds_read2_b32 v[12:13], v2 offset0:195 offset1:227
	v_add_u32_e32 v2, 0x400, v2
	ds_read2_b32 v[14:15], v2 offset0:4 offset1:36
	ds_read2_b32 v[16:17], v2 offset0:69 offset1:101
	ds_read2_b32 v[18:19], v2 offset0:134 offset1:166
	ds_read2_b32 v[20:21], v2 offset0:199 offset1:231
	v_add_u32_e32 v22, s2, v22
	v_ashrrev_i32_e32 v23, 31, v22
	v_lshl_add_u64 v[0:1], s[4:5], 0, v[188:189]
	v_lshlrev_b64 v[24:25], 9, v[22:23]
	s_waitcnt lgkmcnt(6)
	v_cvt_pk_bf16_f32 v2, v6, v8
	s_waitcnt lgkmcnt(4)
	v_cvt_pk_bf16_f32 v3, v10, v12
	s_waitcnt lgkmcnt(2)
	v_cvt_pk_bf16_f32 v4, v14, v16
	s_waitcnt lgkmcnt(0)
	v_cvt_pk_bf16_f32 v5, v18, v20
	v_lshl_add_u64 v[24:25], v[0:1], 0, v[24:25]
	v_add_u32_e32 v6, 32, v22
	global_store_dwordx4 v[24:25], v[2:5], off
	s_nop 1
	v_cvt_pk_bf16_f32 v2, v7, v9
	v_ashrrev_i32_e32 v7, 31, v6
	v_lshlrev_b64 v[6:7], 9, v[6:7]
	v_cvt_pk_bf16_f32 v3, v11, v13
	v_cvt_pk_bf16_f32 v4, v15, v17
	v_cvt_pk_bf16_f32 v5, v19, v21
	v_lshl_add_u64 v[0:1], v[0:1], 0, v[6:7]
	global_store_dwordx4 v[0:1], v[2:5], off

; template <bool MAP = false>
; DI void conv_tile(const float* __restrict__ src, int N, int K, bfu* __restrict__ dst, const float* __restrict__ g,
;                   int tk, int tn, char* smem, int ldk = -1) {
;     ...
;   for (int j = 0; j < 4; ++j) {
;     int k = (tid >> 4) + 16 * j, n4 = (tid & 15) * 4;
;     int gn = tn * 64 + n4, gk = tk * 64 + k;
;     float4 v = make_float4(0.f, 0.f, 0.f, 0.f);
;     const int og = MAP ? in_colmap(gn) : (gn < N ? gn : -1);
;     if (og >= 0) v = *(const float4*)(src + (size_t)gk * N + og);
;     float gg = g ? g[gk] : 1.f;
;     T[k * 65 + n4 + 0] = v.x * gg; T[k * 65 + n4 + 1] = v.y * gg; T[k * 65 + n4 + 2] = v.z * gg; T[k * 65 + n4 + 3] = v.w * gg;
;   }
.LBB0_168:
	s_movk_i32 s5, 0x104
	v_lshlrev_b32_e32 v9, 2, v14
	s_waitcnt vmcnt(0)
	v_pk_mul_f32 v[0:1], v[0:1], v[12:13] op_sel_hi:[1,0]
	v_mul_lo_u32 v13, v13, s5
	v_add_u32_e32 v9, v9, v13
	ds_write2_b32 v9, v0, v1 offset1:1
	v_pk_mul_f32 v[0:1], v[2:3], v[12:13] op_sel_hi:[1,0]
	ds_write2_b32 v9, v0, v1 offset0:2 offset1:3
	v_add_u32_e32 v0, 16, v8
	v_ashrrev_i32_e32 v1, 31, v0
	v_lshlrev_b64 v[0:1], 12, v[0:1]
	v_lshl_add_u64 v[0:1], v[6:7], 0, v[0:1]
	v_mov_b32_e32 v0, v240
	v_mov_b32_e32 v1, v241
	v_mov_b32_e32 v2, v242
	v_mov_b32_e32 v3, v243
	s_and_b64 vcc, exec, s[2:3]
	s_cbranch_vccnz .LBB0_170
	global_load_dword v10, v[4:5], off offset:64
.LBB0_170:
	s_waitcnt vmcnt(0)
	v_pk_mul_f32 v[0:1], v[0:1], v[10:11] op_sel_hi:[1,0]
	v_add_u32_e32 v12, 0x1040, v9
	ds_write2_b32 v12, v0, v1 offset1:1
	v_pk_mul_f32 v[0:1], v[2:3], v[10:11] op_sel_hi:[1,0]
	v_add_u32_e32 v2, 0x1048, v9
	ds_write2_b32 v2, v0, v1 offset1:1
	v_add_u32_e32 v0, 32, v8
	v_ashrrev_i32_e32 v1, 31, v0
	v_lshlrev_b64 v[0:1], 12, v[0:1]
	v_lshl_add_u64 v[0:1], v[6:7], 0, v[0:1]
	v_mov_b32_e32 v0, v244
	v_mov_b32_e32 v1, v245
	v_mov_b32_e32 v2, v246
	v_mov_b32_e32 v3, v247
	v_mov_b32_e32 v10, 1.0
	s_and_b64 vcc, exec, s[2:3]
	v_mov_b32_e32 v12, 1.0
	s_cbranch_vccnz .LBB0_172
	global_load_dword v12, v[4:5], off offset:128
.LBB0_172:
	s_waitcnt vmcnt(0)
	v_pk_mul_f32 v[0:1], v[0:1], v[12:13] op_sel_hi:[1,0]
	v_add_u32_e32 v13, 0x2080, v9
	ds_write2_b32 v13, v0, v1 offset1:1
	v_pk_mul_f32 v[0:1], v[2:3], v[12:13] op_sel_hi:[1,0]
	v_add_u32_e32 v2, 0x2088, v9
	ds_write2_b32 v2, v0, v1 offset1:1
	v_add_u32_e32 v0, 48, v8
	v_ashrrev_i32_e32 v1, 31, v0
	v_lshlrev_b64 v[0:1], 12, v[0:1]
	v_lshl_add_u64 v[0:1], v[6:7], 0, v[0:1]
	v_mov_b32_e32 v0, v248
	v_mov_b32_e32 v1, v249
	v_mov_b32_e32 v2, v250
	v_mov_b32_e32 v3, v251
	s_and_b64 vcc, exec, s[2:3]
	s_cbranch_vccnz .LBB0_174
	global_load_dword v10, v[4:5], off offset:192

; DI int TID() { int t = threadIdx.x; asm volatile("" : "+v"(t)); return t; }
; DI unsigned pk2(float a, float b) { f32x2_t v = {a, b}; bf16x2_t r_ = __builtin_convertvector(v, bf16x2_t); return __builtin_bit_cast(unsigned, r_); }
; template <bool MAP = false>
; DI void conv_tile(const float* __restrict__ src, int N, int K, bfu* __restrict__ dst, const float* __restrict__ g,
;                   int tk, int tn, char* smem, int ldk = -1) {
;     ...
;   float* T = (float*)smem;
;   const int tid = TID();
;   __syncthreads();
; #pragma unroll
;   for (int j = 0; j < 4; ++j) {
;     int k = (tid >> 4) + 16 * j, n4 = (tid & 15) * 4;
;     int gn = tn * 64 + n4, gk = tk * 64 + k;
;     float4 v = make_float4(0.f, 0.f, 0.f, 0.f);
;     const int og = MAP ? in_colmap(gn) : (gn < N ? gn : -1);
;     if (og >= 0) v = *(const float4*)(src + (size_t)gk * N + og);
;     float gg = g ? g[gk] : 1.f;
;     T[k * 65 + n4 + 0] = v.x * gg; T[k * 65 + n4 + 1] = v.y * gg; T[k * 65 + n4 + 2] = v.z * gg; T[k * 65 + n4 + 3] = v.w * gg;
;   }
;   __syncthreads();
; #pragma unroll
;   for (int j = 0; j < 2; ++j) {
;     int n = (tid >> 3) + 32 * j, kc = tid & 7;
;     float e[8];
; #pragma unroll
;     for (int q = 0; q < 8; ++q) e[q] = T[(kc * 8 + q) * 65 + n];
;     u32x4 o = {pk2(e[0], e[1]), pk2(e[2], e[3]), pk2(e[4], e[5]), pk2(e[6], e[7])};
;     *(u32x4*)(dst + (size_t)(tn * 64 + n) * LK + tk * 64 + kc * 8) = o;
;   }
.LBB0_176:
	s_andn2_b64 vcc, exec, s[2:3]
	s_cbranch_vccnz .LBB0_178
	v_mov_b32_e32 v8, v224
	s_lshl_b32 s3, s6, 2
	s_lshl_b32 s2, s6, 6
	v_lshlrev_b32_e32 v0, 2, v8
	s_and_b32 s3, s3, 0x3fc0
	v_ashrrev_i32_e32 v2, 4, v8
	v_and_b32_e32 v3, 60, v0
	s_and_b32 s2, s2, 0x3c0
	s_add_i32 s96, s3, 0xffffe800
	v_or_b32_e32 v0, s2, v3
	v_add_u32_e32 v6, s96, v2
	v_lshlrev_b32_e32 v188, 2, v0
	v_ashrrev_i32_e32 v7, 31, v6
	v_lshl_add_u64 v[4:5], s[90:91], 0, v[188:189]
	v_lshlrev_b64 v[0:1], 12, v[6:7]
	s_movk_i32 s3, 0x104
	v_lshl_add_u64 v[0:1], v[4:5], 0, v[0:1]
	v_mul_lo_u32 v2, v2, s3
	s_waitcnt vmcnt(63) expcnt(7) lgkmcnt(15)
	s_barrier
	v_lshl_add_u32 v7, v3, 2, v2
	v_add_u32_e32 v210, 16, v6
	v_ashrrev_i32_e32 v211, 31, v210
	v_lshlrev_b64 v[210:211], 12, v[210:211]
	v_lshl_add_u64 v[210:211], v[4:5], 0, v[210:211]
	global_load_dwordx4 v[240:243], v[210:211], off
	v_add_u32_e32 v210, 32, v6
	v_ashrrev_i32_e32 v211, 31, v210
	v_lshlrev_b64 v[210:211], 12, v[210:211]
	v_lshl_add_u64 v[210:211], v[4:5], 0, v[210:211]
	global_load_dwordx4 v[244:247], v[210:211], off
	v_add_u32_e32 v210, 48, v6
	v_ashrrev_i32_e32 v211, 31, v210
	v_lshlrev_b64 v[210:211], 12, v[210:211]
	v_lshl_add_u64 v[210:211], v[4:5], 0, v[210:211]
	global_load_dwordx4 v[248:251], v[210:211], off
	global_load_dwordx4 v[0:3], v[0:1], off
	v_add_u32_e32 v9, 0x1040, v7
	v_ashrrev_i32_e32 v22, 3, v8
	v_readlane_b32 s16, v253, 48
	s_lshl_b64 s[4:5], s[96:97], 1
	v_readlane_b32 s26, v253, 58
	v_readlane_b32 s27, v253, 59
	s_add_u32 s4, s26, s4
	s_addc_u32 s5, s27, s5
	v_readlane_b32 s17, v253, 49
	v_readlane_b32 s18, v253, 50
	v_readlane_b32 s19, v253, 51
	v_readlane_b32 s20, v253, 52
	v_readlane_b32 s21, v253, 53
	v_readlane_b32 s22, v253, 54
	v_readlane_b32 s23, v253, 55
	v_readlane_b32 s24, v253, 56
	v_readlane_b32 s25, v253, 57
	v_readlane_b32 s28, v253, 60
	v_readlane_b32 s29, v253, 61
	v_readlane_b32 s30, v253, 62
	v_readlane_b32 s31, v253, 63
	s_waitcnt vmcnt(0)
	ds_write2_b32 v7, v0, v1 offset1:1
	ds_write2_b32 v7, v2, v3 offset0:2 offset1:3
	v_add_u32_e32 v0, 16, v6
	v_ashrrev_i32_e32 v1, 31, v0
	v_lshlrev_b64 v[0:1], 12, v[0:1]
	v_lshl_add_u64 v[0:1], v[4:5], 0, v[0:1]
	v_mov_b32_e32 v0, v240
	v_mov_b32_e32 v1, v241
	v_mov_b32_e32 v2, v242
	v_mov_b32_e32 v3, v243
	s_waitcnt vmcnt(0)
	ds_write2_b32 v9, v0, v1 offset1:1
	v_add_u32_e32 v0, 0x1048, v7
	ds_write2_b32 v0, v2, v3 offset1:1
	v_add_u32_e32 v0, 32, v6
	v_ashrrev_i32_e32 v1, 31, v0
	v_lshlrev_b64 v[0:1], 12, v[0:1]
	v_lshl_add_u64 v[0:1], v[4:5], 0, v[0:1]
	v_mov_b32_e32 v0, v244
	v_mov_b32_e32 v1, v245
	v_mov_b32_e32 v2, v246
	v_mov_b32_e32 v3, v247
	v_add_u32_e32 v9, 0x2080, v7
	s_waitcnt vmcnt(0)
	ds_write2_b32 v9, v0, v1 offset1:1
	v_add_u32_e32 v0, 0x2088, v7
	ds_write2_b32 v0, v2, v3 offset1:1
	v_add_u32_e32 v0, 48, v6
	v_ashrrev_i32_e32 v1, 31, v0
	v_lshlrev_b64 v[0:1], 12, v[0:1]
	v_lshl_add_u64 v[0:1], v[4:5], 0, v[0:1]
	v_mov_b32_e32 v0, v248
	v_mov_b32_e32 v1, v249
	v_mov_b32_e32 v2, v250
	v_mov_b32_e32 v3, v251
	v_add_u32_e32 v4, 0x30c0, v7
	s_waitcnt vmcnt(0)
	ds_write2_b32 v4, v0, v1 offset1:1
	v_add_u32_e32 v0, 0x30c8, v7
	ds_write2_b32 v0, v2, v3 offset1:1
	v_lshlrev_b32_e32 v0, 3, v8
	v_and_b32_e32 v2, 56, v0
	v_lshlrev_b32_e32 v188, 1, v2
	v_mul_u32_u24_e32 v2, 0x104, v2
	v_lshl_add_u32 v2, v22, 2, v2
	s_waitcnt lgkmcnt(0)
	s_barrier
	ds_read2_b32 v[6:7], v2 offset1:32
	ds_read2_b32 v[8:9], v2 offset0:65 offset1:97
	ds_read2_b32 v[10:11], v2 offset0:130 offset1:162
	ds_read2_b32 v[12:13], v2 offset0:195 offset1:227
	v_add_u32_e32 v2, 0x400, v2
	ds_read2_b32 v[14:15], v2 offset0:4 offset1:36
	ds_read2_b32 v[16:17], v2 offset0:69 offset1:101
	ds_read2_b32 v[18:19], v2 offset0:134 offset1:166
	ds_read2_b32 v[20:21], v2 offset0:199 offset1:231
	v_add_u32_e32 v22, s2, v22
	v_ashrrev_i32_e32 v23, 31, v22
	v_lshl_add_u64 v[0:1], s[4:5], 0, v[188:189]
	v_lshlrev_b64 v[24:25], 13, v[22:23]
	s_waitcnt lgkmcnt(6)
	v_cvt_pk_bf16_f32 v2, v6, v8
	s_waitcnt lgkmcnt(4)
	v_cvt_pk_bf16_f32 v3, v10, v12
	s_waitcnt lgkmcnt(2)
	v_cvt_pk_bf16_f32 v4, v14, v16
	s_waitcnt lgkmcnt(0)
	v_cvt_pk_bf16_f32 v5, v18, v20
	v_lshl_add_u64 v[24:25], v[0:1], 0, v[24:25]
	v_add_u32_e32 v6, 32, v22
	global_store_dwordx4 v[24:25], v[2:5], off
	s_nop 1
	v_cvt_pk_bf16_f32 v2, v7, v9
	v_ashrrev_i32_e32 v7, 31, v6
	v_lshlrev_b64 v[6:7], 13, v[6:7]
	v_cvt_pk_bf16_f32 v3, v11, v13
	v_cvt_pk_bf16_f32 v4, v15, v17
	v_cvt_pk_bf16_f32 v5, v19, v21
	v_lshl_add_u64 v[0:1], v[0:1], 0, v[6:7]
	global_store_dwordx4 v[0:1], v[2:5], off

; template <bool MAP = false>
; DI void conv_tile(const float* __restrict__ src, int N, int K, bfu* __restrict__ dst, const float* __restrict__ g,
;                   int tk, int tn, char* smem, int ldk = -1) {
;     ...
;   for (int j = 0; j < 4; ++j) {
;     int k = (tid >> 4) + 16 * j, n4 = (tid & 15) * 4;
;     int gn = tn * 64 + n4, gk = tk * 64 + k;
;     float4 v = make_float4(0.f, 0.f, 0.f, 0.f);
;     const int og = MAP ? in_colmap(gn) : (gn < N ? gn : -1);
;     if (og >= 0) v = *(const float4*)(src + (size_t)gk * N + og);
;     float gg = g ? g[gk] : 1.f;
;     T[k * 65 + n4 + 0] = v.x * gg; T[k * 65 + n4 + 1] = v.y * gg; T[k * 65 + n4 + 2] = v.z * gg; T[k * 65 + n4 + 3] = v.w * gg;
;   }
.LBB0_182:
	s_movk_i32 s4, 0x104
	v_lshlrev_b32_e32 v9, 2, v13
	v_mul_lo_u32 v8, v8, s4
	s_waitcnt vmcnt(0)
	v_pk_mul_f32 v[0:1], v[0:1], v[12:13] op_sel_hi:[1,0]
	v_add_u32_e32 v13, v9, v8
	ds_write2_b32 v13, v0, v1 offset1:1
	v_pk_mul_f32 v[0:1], v[2:3], v[12:13] op_sel_hi:[1,0]
	ds_write2_b32 v13, v0, v1 offset0:2 offset1:3
	v_add_u32_e32 v0, 16, v6
	v_ashrrev_i32_e32 v1, 31, v0
	v_lshlrev_b64 v[0:1], 14, v[0:1]
	v_lshl_add_u64 v[0:1], v[4:5], 0, v[0:1]
	v_mov_b32_e32 v0, v240
	v_mov_b32_e32 v1, v241
	v_mov_b32_e32 v2, v242
	v_mov_b32_e32 v3, v243
	s_and_b64 vcc, exec, s[2:3]
	v_lshl_add_u64 v[8:9], v[6:7], 2, s[52:53]
	s_cbranch_vccnz .LBB0_184
	global_load_dword v10, v[8:9], off offset:64
.LBB0_184:
	s_waitcnt vmcnt(0)
	v_pk_mul_f32 v[0:1], v[0:1], v[10:11] op_sel_hi:[1,0]
	v_add_u32_e32 v7, 0x1040, v13
	ds_write2_b32 v7, v0, v1 offset1:1
	v_pk_mul_f32 v[0:1], v[2:3], v[10:11] op_sel_hi:[1,0]
	v_add_u32_e32 v2, 0x1048, v13
	ds_write2_b32 v2, v0, v1 offset1:1
	v_add_u32_e32 v0, 32, v6
	v_ashrrev_i32_e32 v1, 31, v0
	v_lshlrev_b64 v[0:1], 14, v[0:1]
	v_lshl_add_u64 v[0:1], v[4:5], 0, v[0:1]
	v_mov_b32_e32 v0, v244
	v_mov_b32_e32 v1, v245
	v_mov_b32_e32 v2, v246
	v_mov_b32_e32 v3, v247
	v_mov_b32_e32 v10, 1.0
	s_and_b64 vcc, exec, s[2:3]
	v_mov_b32_e32 v12, 1.0
	s_cbranch_vccnz .LBB0_186
	global_load_dword v12, v[8:9], off offset:128
.LBB0_186:
	s_waitcnt vmcnt(0)
	v_pk_mul_f32 v[0:1], v[0:1], v[12:13] op_sel_hi:[1,0]
	v_add_u32_e32 v7, 0x2080, v13
	ds_write2_b32 v7, v0, v1 offset1:1
	v_pk_mul_f32 v[0:1], v[2:3], v[12:13] op_sel_hi:[1,0]
	v_add_u32_e32 v2, 0x2088, v13
	ds_write2_b32 v2, v0, v1 offset1:1
	v_add_u32_e32 v0, 48, v6
	v_ashrrev_i32_e32 v1, 31, v0
	v_lshlrev_b64 v[0:1], 14, v[0:1]
	v_lshl_add_u64 v[0:1], v[4:5], 0, v[0:1]
	v_mov_b32_e32 v0, v248
	v_mov_b32_e32 v1, v249
	v_mov_b32_e32 v2, v250
	v_mov_b32_e32 v3, v251
	s_and_b64 vcc, exec, s[2:3]
	s_cbranch_vccnz .LBB0_188
	global_load_dword v10, v[8:9], off offset:192

; DI int TID() { int t = threadIdx.x; asm volatile("" : "+v"(t)); return t; }
; DI unsigned pk2(float a, float b) { f32x2_t v = {a, b}; bf16x2_t r_ = __builtin_convertvector(v, bf16x2_t); return __builtin_bit_cast(unsigned, r_); }
; template <bool MAP = false>
; DI void conv_tile(const float* __restrict__ src, int N, int K, bfu* __restrict__ dst, const float* __restrict__ g,
;                   int tk, int tn, char* smem, int ldk = -1) {
;     ...
;   float* T = (float*)smem;
;   const int tid = TID();
;   __syncthreads();
; #pragma unroll
;   for (int j = 0; j < 4; ++j) {
;     int k = (tid >> 4) + 16 * j, n4 = (tid & 15) * 4;
;     int gn = tn * 64 + n4, gk = tk * 64 + k;
;     float4 v = make_float4(0.f, 0.f, 0.f, 0.f);
;     const int og = MAP ? in_colmap(gn) : (gn < N ? gn : -1);
;     if (og >= 0) v = *(const float4*)(src + (size_t)gk * N + og);
;     float gg = g ? g[gk] : 1.f;
;     T[k * 65 + n4 + 0] = v.x * gg; T[k * 65 + n4 + 1] = v.y * gg; T[k * 65 + n4 + 2] = v.z * gg; T[k * 65 + n4 + 3] = v.w * gg;
;   }
;   __syncthreads();
; #pragma unroll
;   for (int j = 0; j < 2; ++j) {
;     int n = (tid >> 3) + 32 * j, kc = tid & 7;
;     float e[8];
; #pragma unroll
;     for (int q = 0; q < 8; ++q) e[q] = T[(kc * 8 + q) * 65 + n];
;     u32x4 o = {pk2(e[0], e[1]), pk2(e[2], e[3]), pk2(e[4], e[5]), pk2(e[6], e[7])};
;     *(u32x4*)(dst + (size_t)(tn * 64 + n) * LK + tk * 64 + kc * 8) = o;
;   }
.LBB0_190:
	s_andn2_b64 vcc, exec, s[2:3]
	s_cbranch_vccnz .LBB0_192
	v_mov_b32_e32 v8, v224
	s_lshl_b32 s3, s6, 2
	s_lshl_b32 s2, s6, 6
	v_lshlrev_b32_e32 v0, 2, v8
	s_and_b32 s3, s3, 0x7c0
	v_ashrrev_i32_e32 v2, 4, v8
	v_and_b32_e32 v3, 60, v0
	s_and_b32 s2, s2, 0x3c0
	s_add_i32 s96, s3, 0xfffffc00
	v_or_b32_e32 v0, s2, v3
	v_readlane_b32 s4, v255, 28
	v_add_u32_e32 v6, s96, v2
	v_lshlrev_b32_e32 v188, 2, v0
	v_readlane_b32 s5, v255, 29
	v_ashrrev_i32_e32 v7, 31, v6
	v_lshlrev_b64 v[0:1], 12, v[6:7]
	v_lshl_add_u64 v[4:5], s[4:5], 0, v[188:189]
	s_movk_i32 s3, 0x104
	v_lshl_add_u64 v[0:1], v[4:5], 0, v[0:1]
	v_mul_lo_u32 v2, v2, s3
	s_waitcnt vmcnt(63) expcnt(7) lgkmcnt(15)
	s_barrier
	v_lshl_add_u32 v7, v3, 2, v2
	v_add_u32_e32 v210, 16, v6
	v_ashrrev_i32_e32 v211, 31, v210
	v_lshlrev_b64 v[210:211], 12, v[210:211]
	v_lshl_add_u64 v[210:211], v[4:5], 0, v[210:211]
	global_load_dwordx4 v[240:243], v[210:211], off
	v_add_u32_e32 v210, 32, v6
	v_ashrrev_i32_e32 v211, 31, v210
	v_lshlrev_b64 v[210:211], 12, v[210:211]
	v_lshl_add_u64 v[210:211], v[4:5], 0, v[210:211]
	global_load_dwordx4 v[244:247], v[210:211], off
	v_add_u32_e32 v210, 48, v6
	v_ashrrev_i32_e32 v211, 31, v210
	v_lshlrev_b64 v[210:211], 12, v[210:211]
	v_lshl_add_u64 v[210:211], v[4:5], 0, v[210:211]
	global_load_dwordx4 v[248:251], v[210:211], off
	global_load_dwordx4 v[0:3], v[0:1], off
	v_add_u32_e32 v9, 0x1040, v7
	v_ashrrev_i32_e32 v22, 3, v8
	v_readlane_b32 s16, v253, 48
	s_lshl_b64 s[4:5], s[96:97], 1
	v_readlane_b32 s22, v253, 54
	v_readlane_b32 s23, v253, 55
	s_add_u32 s4, s22, s4
	s_addc_u32 s5, s23, s5
	v_readlane_b32 s17, v253, 49
	v_readlane_b32 s18, v253, 50
	v_readlane_b32 s19, v253, 51
	v_readlane_b32 s20, v253, 52
	v_readlane_b32 s21, v253, 53
	v_readlane_b32 s24, v253, 56
	v_readlane_b32 s25, v253, 57
	v_readlane_b32 s26, v253, 58
	v_readlane_b32 s27, v253, 59
	v_readlane_b32 s28, v253, 60
	v_readlane_b32 s29, v253, 61
	v_readlane_b32 s30, v253, 62
	v_readlane_b32 s31, v253, 63
	s_waitcnt vmcnt(0)
	ds_write2_b32 v7, v0, v1 offset1:1
	ds_write2_b32 v7, v2, v3 offset0:2 offset1:3
	v_add_u32_e32 v0, 16, v6
	v_ashrrev_i32_e32 v1, 31, v0
	v_lshlrev_b64 v[0:1], 12, v[0:1]
	v_lshl_add_u64 v[0:1], v[4:5], 0, v[0:1]
	v_mov_b32_e32 v0, v240
	v_mov_b32_e32 v1, v241
	v_mov_b32_e32 v2, v242
	v_mov_b32_e32 v3, v243
	s_waitcnt vmcnt(0)
	ds_write2_b32 v9, v0, v1 offset1:1
	v_add_u32_e32 v0, 0x1048, v7
	ds_write2_b32 v0, v2, v3 offset1:1
	v_add_u32_e32 v0, 32, v6
	v_ashrrev_i32_e32 v1, 31, v0
	v_lshlrev_b64 v[0:1], 12, v[0:1]
	v_lshl_add_u64 v[0:1], v[4:5], 0, v[0:1]
	v_mov_b32_e32 v0, v244
	v_mov_b32_e32 v1, v245
	v_mov_b32_e32 v2, v246
	v_mov_b32_e32 v3, v247
	v_add_u32_e32 v9, 0x2080, v7
	s_waitcnt vmcnt(0)
	ds_write2_b32 v9, v0, v1 offset1:1
	v_add_u32_e32 v0, 0x2088, v7
	ds_write2_b32 v0, v2, v3 offset1:1
	v_add_u32_e32 v0, 48, v6
	v_ashrrev_i32_e32 v1, 31, v0
	v_lshlrev_b64 v[0:1], 12, v[0:1]
	v_lshl_add_u64 v[0:1], v[4:5], 0, v[0:1]
	v_mov_b32_e32 v0, v248
	v_mov_b32_e32 v1, v249
	v_mov_b32_e32 v2, v250
	v_mov_b32_e32 v3, v251
	v_add_u32_e32 v4, 0x30c0, v7
	s_waitcnt vmcnt(0)
	ds_write2_b32 v4, v0, v1 offset1:1
	v_add_u32_e32 v0, 0x30c8, v7
	ds_write2_b32 v0, v2, v3 offset1:1
	v_lshlrev_b32_e32 v0, 3, v8
	v_and_b32_e32 v2, 56, v0
	v_lshlrev_b32_e32 v188, 1, v2
	v_mul_u32_u24_e32 v2, 0x104, v2
	v_lshl_add_u32 v2, v22, 2, v2
	s_waitcnt lgkmcnt(0)
	s_barrier
	ds_read2_b32 v[6:7], v2 offset1:32
	ds_read2_b32 v[8:9], v2 offset0:65 offset1:97
	ds_read2_b32 v[10:11], v2 offset0:130 offset1:162
	ds_read2_b32 v[12:13], v2 offset0:195 offset1:227
	v_add_u32_e32 v2, 0x400, v2
	ds_read2_b32 v[14:15], v2 offset0:4 offset1:36
	ds_read2_b32 v[16:17], v2 offset0:69 offset1:101
	ds_read2_b32 v[18:19], v2 offset0:134 offset1:166
	ds_read2_b32 v[20:21], v2 offset0:199 offset1:231
	v_add_u32_e32 v22, s2, v22
	v_ashrrev_i32_e32 v23, 31, v22
	v_lshl_add_u64 v[0:1], s[4:5], 0, v[188:189]
	v_lshlrev_b64 v[24:25], 11, v[22:23]
	s_waitcnt lgkmcnt(6)
	v_cvt_pk_bf16_f32 v2, v6, v8
	s_waitcnt lgkmcnt(4)
	v_cvt_pk_bf16_f32 v3, v10, v12
	s_waitcnt lgkmcnt(2)
	v_cvt_pk_bf16_f32 v4, v14, v16
	s_waitcnt lgkmcnt(0)
	v_cvt_pk_bf16_f32 v5, v18, v20
	v_lshl_add_u64 v[24:25], v[0:1], 0, v[24:25]
	v_add_u32_e32 v6, 32, v22
	global_store_dwordx4 v[24:25], v[2:5], off
	s_nop 1
	v_cvt_pk_bf16_f32 v2, v7, v9
	v_ashrrev_i32_e32 v7, 31, v6
	v_lshlrev_b64 v[6:7], 11, v[6:7]
	v_cvt_pk_bf16_f32 v3, v11, v13
	v_cvt_pk_bf16_f32 v4, v15, v17
	v_cvt_pk_bf16_f32 v5, v19, v21
	v_lshl_add_u64 v[0:1], v[0:1], 0, v[6:7]
	global_store_dwordx4 v[0:1], v[2:5], off

; DI int TID() { int t = threadIdx.x; asm volatile("" : "+v"(t)); return t; }
; DI unsigned pk2(float a, float b) { f32x2_t v = {a, b}; bf16x2_t r_ = __builtin_convertvector(v, bf16x2_t); return __builtin_bit_cast(unsigned, r_); }
; template <bool MAP = false>
; DI void conv_tile(const float* __restrict__ src, int N, int K, bfu* __restrict__ dst, const float* __restrict__ g,
;                   int tk, int tn, char* smem, int ldk = -1) {
;     ...
;   float* T = (float*)smem;
;   const int tid = TID();
;   __syncthreads();
; #pragma unroll
;   for (int j = 0; j < 4; ++j) {
;     int k = (tid >> 4) + 16 * j, n4 = (tid & 15) * 4;
;     int gn = tn * 64 + n4, gk = tk * 64 + k;
;     float4 v = make_float4(0.f, 0.f, 0.f, 0.f);
;     const int og = MAP ? in_colmap(gn) : (gn < N ? gn : -1);
;     if (og >= 0) v = *(const float4*)(src + (size_t)gk * N + og);
;     float gg = g ? g[gk] : 1.f;
;     T[k * 65 + n4 + 0] = v.x * gg; T[k * 65 + n4 + 1] = v.y * gg; T[k * 65 + n4 + 2] = v.z * gg; T[k * 65 + n4 + 3] = v.w * gg;
;   }
;   __syncthreads();
; #pragma unroll
;   for (int j = 0; j < 2; ++j) {
;     int n = (tid >> 3) + 32 * j, kc = tid & 7;
;     float e[8];
; #pragma unroll
;     for (int q = 0; q < 8; ++q) e[q] = T[(kc * 8 + q) * 65 + n];
;     u32x4 o = {pk2(e[0], e[1]), pk2(e[2], e[3]), pk2(e[4], e[5]), pk2(e[6], e[7])};
;     *(u32x4*)(dst + (size_t)(tn * 64 + n) * LK + tk * 64 + kc * 8) = o;
;   }
; DI void conv_item_C(const Params& p, int L, int it, char* smem) {
;   if (it < 256) { int t = it; int n = t >> 6; t &= 63; conv_tile(p.w_branch + ((size_t)L * 4 + n) * 256 * D, D, 256, p.wt_br + (size_t)n * 256, nullptr, t / 16, t % 16, smem, 1024); }
.LBB0_193:
	s_andn2_b64 vcc, exec, s[2:3]
	s_cbranch_vccnz .LBB0_195
	s_lshr_b32 s96, s6, 6
	s_lshl_b64 s[2:3], s[96:97], 20
	s_add_u32 s4, s61, s2
	v_readlane_b32 s16, v253, 48
	s_addc_u32 s5, s89, s3
	s_lshl_b64 s[2:3], s[96:97], 9
	v_readlane_b32 s20, v253, 52
	v_readlane_b32 s21, v253, 53
	s_add_u32 s7, s20, s2
	v_mov_b32_e32 v8, v224
	s_addc_u32 s3, s21, s3
	s_lshl_b32 s2, s6, 6
	v_lshlrev_b32_e32 v0, 2, v8
	s_lshl_b32 s6, s6, 2
	v_ashrrev_i32_e32 v2, 4, v8
	v_and_b32_e32 v3, 60, v0
	s_and_b32 s2, s2, 0x3c0
	s_and_b32 s6, s6, 0xc0
	v_or_b32_e32 v0, s2, v3
	v_add_u32_e32 v6, s6, v2
	v_lshlrev_b32_e32 v188, 2, v0
	v_ashrrev_i32_e32 v7, 31, v6
	v_lshl_add_u64 v[4:5], s[4:5], 0, v[188:189]
	v_lshlrev_b64 v[0:1], 12, v[6:7]
	s_movk_i32 s4, 0x104
	v_lshl_add_u64 v[0:1], v[4:5], 0, v[0:1]
	v_mul_lo_u32 v2, v2, s4
	s_waitcnt vmcnt(63) expcnt(7) lgkmcnt(15)
	s_barrier
	v_lshl_add_u32 v7, v3, 2, v2
	v_add_u32_e32 v210, 16, v6
	v_ashrrev_i32_e32 v211, 31, v210
	v_lshlrev_b64 v[210:211], 12, v[210:211]
	v_lshl_add_u64 v[210:211], v[4:5], 0, v[210:211]
	global_load_dwordx4 v[240:243], v[210:211], off
	v_add_u32_e32 v210, 32, v6
	v_ashrrev_i32_e32 v211, 31, v210
	v_lshlrev_b64 v[210:211], 12, v[210:211]
	v_lshl_add_u64 v[210:211], v[4:5], 0, v[210:211]
	global_load_dwordx4 v[244:247], v[210:211], off
	v_add_u32_e32 v210, 48, v6
	v_ashrrev_i32_e32 v211, 31, v210
	v_lshlrev_b64 v[210:211], 12, v[210:211]
	v_lshl_add_u64 v[210:211], v[4:5], 0, v[210:211]
	global_load_dwordx4 v[248:251], v[210:211], off
	global_load_dwordx4 v[0:3], v[0:1], off
	v_add_u32_e32 v9, 0x1040, v7
	v_ashrrev_i32_e32 v22, 3, v8
	s_lshl_b32 s4, s6, 1
	s_add_u32 s4, s7, s4
	s_addc_u32 s5, s3, 0
	v_readlane_b32 s17, v253, 49
	v_readlane_b32 s18, v253, 50
	v_readlane_b32 s19, v253, 51
	v_readlane_b32 s22, v253, 54
	v_readlane_b32 s23, v253, 55
	v_readlane_b32 s24, v253, 56
	v_readlane_b32 s25, v253, 57
	v_readlane_b32 s26, v253, 58
	v_readlane_b32 s27, v253, 59
	v_readlane_b32 s28, v253, 60
	v_readlane_b32 s29, v253, 61
	v_readlane_b32 s30, v253, 62
	v_readlane_b32 s31, v253, 63
	s_waitcnt vmcnt(0)
	ds_write2_b32 v7, v0, v1 offset1:1
	ds_write2_b32 v7, v2, v3 offset0:2 offset1:3
	v_add_u32_e32 v0, 16, v6
	v_ashrrev_i32_e32 v1, 31, v0
	v_lshlrev_b64 v[0:1], 12, v[0:1]
	v_lshl_add_u64 v[0:1], v[4:5], 0, v[0:1]
	v_mov_b32_e32 v0, v240
	v_mov_b32_e32 v1, v241
	v_mov_b32_e32 v2, v242
	v_mov_b32_e32 v3, v243
	s_waitcnt vmcnt(0)
	ds_write2_b32 v9, v0, v1 offset1:1
	v_add_u32_e32 v0, 0x1048, v7
	ds_write2_b32 v0, v2, v3 offset1:1
	v_add_u32_e32 v0, 32, v6
	v_ashrrev_i32_e32 v1, 31, v0
	v_lshlrev_b64 v[0:1], 12, v[0:1]
	v_lshl_add_u64 v[0:1], v[4:5], 0, v[0:1]
	v_mov_b32_e32 v0, v244
	v_mov_b32_e32 v1, v245
	v_mov_b32_e32 v2, v246
	v_mov_b32_e32 v3, v247
	v_add_u32_e32 v9, 0x2080, v7
	s_waitcnt vmcnt(0)
	ds_write2_b32 v9, v0, v1 offset1:1
	v_add_u32_e32 v0, 0x2088, v7
	ds_write2_b32 v0, v2, v3 offset1:1
	v_add_u32_e32 v0, 48, v6
	v_ashrrev_i32_e32 v1, 31, v0
	v_lshlrev_b64 v[0:1], 12, v[0:1]
	v_lshl_add_u64 v[0:1], v[4:5], 0, v[0:1]
	v_mov_b32_e32 v0, v248
	v_mov_b32_e32 v1, v249
	v_mov_b32_e32 v2, v250
	v_mov_b32_e32 v3, v251
	v_add_u32_e32 v4, 0x30c0, v7
	s_waitcnt vmcnt(0)
	ds_write2_b32 v4, v0, v1 offset1:1
	v_add_u32_e32 v0, 0x30c8, v7
	ds_write2_b32 v0, v2, v3 offset1:1
	v_lshlrev_b32_e32 v0, 3, v8
	v_and_b32_e32 v2, 56, v0
	v_lshlrev_b32_e32 v188, 1, v2
	v_mul_u32_u24_e32 v2, 0x104, v2
	v_lshl_add_u32 v2, v22, 2, v2
	s_waitcnt lgkmcnt(0)
	s_barrier
	ds_read2_b32 v[6:7], v2 offset1:32
	ds_read2_b32 v[8:9], v2 offset0:65 offset1:97
	ds_read2_b32 v[10:11], v2 offset0:130 offset1:162
	ds_read2_b32 v[12:13], v2 offset0:195 offset1:227
	v_add_u32_e32 v2, 0x400, v2
	ds_read2_b32 v[14:15], v2 offset0:4 offset1:36
	ds_read2_b32 v[16:17], v2 offset0:69 offset1:101
	ds_read2_b32 v[18:19], v2 offset0:134 offset1:166
	ds_read2_b32 v[20:21], v2 offset0:199 offset1:231
	v_add_u32_e32 v22, s2, v22
	v_ashrrev_i32_e32 v23, 31, v22
	v_lshl_add_u64 v[0:1], s[4:5], 0, v[188:189]
	v_lshlrev_b64 v[24:25], 11, v[22:23]
	s_waitcnt lgkmcnt(6)
	v_cvt_pk_bf16_f32 v2, v6, v8
	s_waitcnt lgkmcnt(4)
	v_cvt_pk_bf16_f32 v3, v10, v12
	s_waitcnt lgkmcnt(2)
	v_cvt_pk_bf16_f32 v4, v14, v16
	s_waitcnt lgkmcnt(0)
	v_cvt_pk_bf16_f32 v5, v18, v20
	v_lshl_add_u64 v[24:25], v[0:1], 0, v[24:25]
	v_add_u32_e32 v6, 32, v22
	global_store_dwordx4 v[24:25], v[2:5], off
	s_nop 1
	v_cvt_pk_bf16_f32 v2, v7, v9
	v_ashrrev_i32_e32 v7, 31, v6
	v_lshlrev_b64 v[6:7], 11, v[6:7]
	v_cvt_pk_bf16_f32 v3, v11, v13
	v_cvt_pk_bf16_f32 v4, v15, v17
	v_cvt_pk_bf16_f32 v5, v19, v21
	v_lshl_add_u64 v[0:1], v[0:1], 0, v[6:7]
	global_store_dwordx4 v[0:1], v[2:5], off

; DI int TID() { int t = threadIdx.x; asm volatile("" : "+v"(t)); return t; }
; DI unsigned pk2(float a, float b) { f32x2_t v = {a, b}; bf16x2_t r_ = __builtin_convertvector(v, bf16x2_t); return __builtin_bit_cast(unsigned, r_); }
; template <bool MAP = false>
; DI void conv_tile(const float* __restrict__ src, int N, int K, bfu* __restrict__ dst, const float* __restrict__ g,
;                   int tk, int tn, char* smem, int ldk = -1) {
;     ...
;   float* T = (float*)smem;
;   const int tid = TID();
;   __syncthreads();
; #pragma unroll
;   for (int j = 0; j < 4; ++j) {
;     int k = (tid >> 4) + 16 * j, n4 = (tid & 15) * 4;
;     int gn = tn * 64 + n4, gk = tk * 64 + k;
;     float4 v = make_float4(0.f, 0.f, 0.f, 0.f);
;     const int og = MAP ? in_colmap(gn) : (gn < N ? gn : -1);
;     if (og >= 0) v = *(const float4*)(src + (size_t)gk * N + og);
;     float gg = g ? g[gk] : 1.f;
;     T[k * 65 + n4 + 0] = v.x * gg; T[k * 65 + n4 + 1] = v.y * gg; T[k * 65 + n4 + 2] = v.z * gg; T[k * 65 + n4 + 3] = v.w * gg;
;   }
;   __syncthreads();
; #pragma unroll
;   for (int j = 0; j < 2; ++j) {
;     int n = (tid >> 3) + 32 * j, kc = tid & 7;
;     float e[8];
; #pragma unroll
;     for (int q = 0; q < 8; ++q) e[q] = T[(kc * 8 + q) * 65 + n];
;     u32x4 o = {pk2(e[0], e[1]), pk2(e[2], e[3]), pk2(e[4], e[5]), pk2(e[6], e[7])};
;     *(u32x4*)(dst + (size_t)(tn * 64 + n) * LK + tk * 64 + kc * 8) = o;
;   }
.LBB0_1918:
	s_andn2_b64 vcc, exec, s[2:3]
	s_cbranch_vccnz .LBB0_1920
	v_mov_b32_e32 v8, v224
	s_lshl_b32 s3, s12, 2
	s_lshl_b32 s2, s12, 6
	v_lshlrev_b32_e32 v0, 2, v8
	s_and_b32 s3, s3, 0x3fc0
	v_ashrrev_i32_e32 v2, 4, v8
	v_and_b32_e32 v3, 60, v0
	s_and_b32 s2, s2, 0x3c0
	s_add_i32 s96, s3, 0xffffd400
	v_or_b32_e32 v0, s2, v3
	v_add_u32_e32 v6, s96, v2
	v_lshlrev_b32_e32 v188, 2, v0
	v_ashrrev_i32_e32 v7, 31, v6
	v_lshl_add_u64 v[4:5], s[62:63], 0, v[188:189]
	v_lshlrev_b64 v[0:1], 12, v[6:7]
	s_movk_i32 s3, 0x104
	v_lshl_add_u64 v[0:1], v[4:5], 0, v[0:1]
	v_mul_lo_u32 v2, v2, s3
	s_waitcnt vmcnt(63) expcnt(7) lgkmcnt(15)
	s_barrier
	v_lshl_add_u32 v7, v3, 2, v2
	v_add_u32_e32 v210, 16, v6
	v_ashrrev_i32_e32 v211, 31, v210
	v_lshlrev_b64 v[210:211], 12, v[210:211]
	v_lshl_add_u64 v[210:211], v[4:5], 0, v[210:211]
	global_load_dwordx4 v[240:243], v[210:211], off
	v_add_u32_e32 v210, 32, v6
	v_ashrrev_i32_e32 v211, 31, v210
	v_lshlrev_b64 v[210:211], 12, v[210:211]
	v_lshl_add_u64 v[210:211], v[4:5], 0, v[210:211]
	global_load_dwordx4 v[244:247], v[210:211], off
	v_add_u32_e32 v210, 48, v6
	v_ashrrev_i32_e32 v211, 31, v210
	v_lshlrev_b64 v[210:211], 12, v[210:211]
	v_lshl_add_u64 v[210:211], v[4:5], 0, v[210:211]
	global_load_dwordx4 v[248:251], v[210:211], off
	global_load_dwordx4 v[0:3], v[0:1], off
	v_add_u32_e32 v9, 0x1040, v7
	v_ashrrev_i32_e32 v22, 3, v8
	v_readlane_b32 s16, v253, 48
	s_lshl_b64 s[4:5], s[96:97], 1
	v_readlane_b32 s30, v253, 62
	v_readlane_b32 s31, v253, 63
	s_add_u32 s4, s30, s4
	s_addc_u32 s5, s31, s5
	v_readlane_b32 s17, v253, 49
	v_readlane_b32 s18, v253, 50
	v_readlane_b32 s19, v253, 51
	v_readlane_b32 s20, v253, 52
	v_readlane_b32 s21, v253, 53
	v_readlane_b32 s22, v253, 54
	v_readlane_b32 s23, v253, 55
	v_readlane_b32 s24, v253, 56
	v_readlane_b32 s25, v253, 57
	v_readlane_b32 s26, v253, 58
	v_readlane_b32 s27, v253, 59
	v_readlane_b32 s28, v253, 60
	v_readlane_b32 s29, v253, 61
	s_waitcnt vmcnt(0)
	ds_write2_b32 v7, v0, v1 offset1:1
	ds_write2_b32 v7, v2, v3 offset0:2 offset1:3
	v_add_u32_e32 v0, 16, v6
	v_ashrrev_i32_e32 v1, 31, v0
	v_lshlrev_b64 v[0:1], 12, v[0:1]
	v_lshl_add_u64 v[0:1], v[4:5], 0, v[0:1]
	v_mov_b32_e32 v0, v240
	v_mov_b32_e32 v1, v241
	v_mov_b32_e32 v2, v242
	v_mov_b32_e32 v3, v243
	s_waitcnt vmcnt(0)
	ds_write2_b32 v9, v0, v1 offset1:1
	v_add_u32_e32 v0, 0x1048, v7
	ds_write2_b32 v0, v2, v3 offset1:1
	v_add_u32_e32 v0, 32, v6
	v_ashrrev_i32_e32 v1, 31, v0
	v_lshlrev_b64 v[0:1], 12, v[0:1]
	v_lshl_add_u64 v[0:1], v[4:5], 0, v[0:1]
	v_mov_b32_e32 v0, v244
	v_mov_b32_e32 v1, v245
	v_mov_b32_e32 v2, v246
	v_mov_b32_e32 v3, v247
	v_add_u32_e32 v9, 0x2080, v7
	s_waitcnt vmcnt(0)
	ds_write2_b32 v9, v0, v1 offset1:1
	v_add_u32_e32 v0, 0x2088, v7
	ds_write2_b32 v0, v2, v3 offset1:1
	v_add_u32_e32 v0, 48, v6
	v_ashrrev_i32_e32 v1, 31, v0
	v_lshlrev_b64 v[0:1], 12, v[0:1]
	v_lshl_add_u64 v[0:1], v[4:5], 0, v[0:1]
	v_mov_b32_e32 v0, v248
	v_mov_b32_e32 v1, v249
	v_mov_b32_e32 v2, v250
	v_mov_b32_e32 v3, v251
	v_add_u32_e32 v4, 0x30c0, v7
	s_waitcnt vmcnt(0)
	ds_write2_b32 v4, v0, v1 offset1:1
	v_add_u32_e32 v0, 0x30c8, v7
	ds_write2_b32 v0, v2, v3 offset1:1
	v_lshlrev_b32_e32 v0, 3, v8
	v_and_b32_e32 v2, 56, v0
	v_lshlrev_b32_e32 v188, 1, v2
	v_mul_u32_u24_e32 v2, 0x104, v2
	v_lshl_add_u32 v2, v22, 2, v2
	s_waitcnt lgkmcnt(0)
	s_barrier
	ds_read2_b32 v[6:7], v2 offset1:32
	ds_read2_b32 v[8:9], v2 offset0:65 offset1:97
	ds_read2_b32 v[10:11], v2 offset0:130 offset1:162
	ds_read2_b32 v[12:13], v2 offset0:195 offset1:227
	v_add_u32_e32 v2, 0x400, v2
	ds_read2_b32 v[14:15], v2 offset0:4 offset1:36
	ds_read2_b32 v[16:17], v2 offset0:69 offset1:101
	ds_read2_b32 v[18:19], v2 offset0:134 offset1:166
	ds_read2_b32 v[20:21], v2 offset0:199 offset1:231
	v_add_u32_e32 v22, s2, v22
	v_ashrrev_i32_e32 v23, 31, v22
	v_lshl_add_u64 v[0:1], s[4:5], 0, v[188:189]
	v_lshlrev_b64 v[24:25], 9, v[22:23]
	s_waitcnt lgkmcnt(6)
	v_cvt_pk_bf16_f32 v2, v6, v8
	s_waitcnt lgkmcnt(4)
	v_cvt_pk_bf16_f32 v3, v10, v12
	s_waitcnt lgkmcnt(2)
	v_cvt_pk_bf16_f32 v4, v14, v16
	s_waitcnt lgkmcnt(0)
	v_cvt_pk_bf16_f32 v5, v18, v20
	v_lshl_add_u64 v[24:25], v[0:1], 0, v[24:25]
	v_add_u32_e32 v6, 32, v22
	global_store_dwordx4 v[24:25], v[2:5], off
	s_nop 1
	v_cvt_pk_bf16_f32 v2, v7, v9
	v_ashrrev_i32_e32 v7, 31, v6
	v_lshlrev_b64 v[6:7], 9, v[6:7]
	v_cvt_pk_bf16_f32 v3, v11, v13
	v_cvt_pk_bf16_f32 v4, v15, v17
	v_cvt_pk_bf16_f32 v5, v19, v21
	v_lshl_add_u64 v[0:1], v[0:1], 0, v[6:7]
	global_store_dwordx4 v[0:1], v[2:5], off

; DI int TID() { int t = threadIdx.x; asm volatile("" : "+v"(t)); return t; }
; DI unsigned pk2(float a, float b) { f32x2_t v = {a, b}; bf16x2_t r_ = __builtin_convertvector(v, bf16x2_t); return __builtin_bit_cast(unsigned, r_); }
; template <bool MAP = false>
; DI void conv_tile(const float* __restrict__ src, int N, int K, bfu* __restrict__ dst, const float* __restrict__ g,
;                   int tk, int tn, char* smem, int ldk = -1) {
;     ...
;   float* T = (float*)smem;
;   const int tid = TID();
;   __syncthreads();
; #pragma unroll
;   for (int j = 0; j < 4; ++j) {
;     int k = (tid >> 4) + 16 * j, n4 = (tid & 15) * 4;
;     int gn = tn * 64 + n4, gk = tk * 64 + k;
;     float4 v = make_float4(0.f, 0.f, 0.f, 0.f);
;     const int og = MAP ? in_colmap(gn) : (gn < N ? gn : -1);
;     if (og >= 0) v = *(const float4*)(src + (size_t)gk * N + og);
;     float gg = g ? g[gk] : 1.f;
;     T[k * 65 + n4 + 0] = v.x * gg; T[k * 65 + n4 + 1] = v.y * gg; T[k * 65 + n4 + 2] = v.z * gg; T[k * 65 + n4 + 3] = v.w * gg;
;   }
;   __syncthreads();
; #pragma unroll
;   for (int j = 0; j < 2; ++j) {
;     int n = (tid >> 3) + 32 * j, kc = tid & 7;
;     float e[8];
; #pragma unroll
;     for (int q = 0; q < 8; ++q) e[q] = T[(kc * 8 + q) * 65 + n];
;     u32x4 o = {pk2(e[0], e[1]), pk2(e[2], e[3]), pk2(e[4], e[5]), pk2(e[6], e[7])};
;     *(u32x4*)(dst + (size_t)(tn * 64 + n) * LK + tk * 64 + kc * 8) = o;
;   }
.LBB0_1932:
	s_andn2_b64 vcc, exec, s[2:3]
	s_cbranch_vccnz .LBB0_1934
	v_mov_b32_e32 v8, v224
	s_lshl_b32 s3, s12, 2
	s_lshl_b32 s2, s12, 6
	v_lshlrev_b32_e32 v0, 2, v8
	s_and_b32 s3, s3, 0x3fc0
	v_ashrrev_i32_e32 v2, 4, v8
	v_and_b32_e32 v3, 60, v0
	s_and_b32 s2, s2, 0x3c0
	s_add_i32 s96, s3, 0xffffe800
	v_or_b32_e32 v0, s2, v3
	v_add_u32_e32 v6, s96, v2
	v_lshlrev_b32_e32 v188, 2, v0
	v_ashrrev_i32_e32 v7, 31, v6
	v_lshl_add_u64 v[4:5], s[92:93], 0, v[188:189]
	v_lshlrev_b64 v[0:1], 12, v[6:7]
	s_movk_i32 s3, 0x104
	v_lshl_add_u64 v[0:1], v[4:5], 0, v[0:1]
	v_mul_lo_u32 v2, v2, s3
	s_waitcnt vmcnt(63) expcnt(7) lgkmcnt(15)
	s_barrier
	v_lshl_add_u32 v7, v3, 2, v2
	v_add_u32_e32 v210, 16, v6
	v_ashrrev_i32_e32 v211, 31, v210
	v_lshlrev_b64 v[210:211], 12, v[210:211]
	v_lshl_add_u64 v[210:211], v[4:5], 0, v[210:211]
	global_load_dwordx4 v[240:243], v[210:211], off
	v_add_u32_e32 v210, 32, v6
	v_ashrrev_i32_e32 v211, 31, v210
	v_lshlrev_b64 v[210:211], 12, v[210:211]
	v_lshl_add_u64 v[210:211], v[4:5], 0, v[210:211]
	global_load_dwordx4 v[244:247], v[210:211], off
	v_add_u32_e32 v210, 48, v6
	v_ashrrev_i32_e32 v211, 31, v210
	v_lshlrev_b64 v[210:211], 12, v[210:211]
	v_lshl_add_u64 v[210:211], v[4:5], 0, v[210:211]
	global_load_dwordx4 v[248:251], v[210:211], off
	global_load_dwordx4 v[0:3], v[0:1], off
	v_add_u32_e32 v9, 0x1040, v7
	v_ashrrev_i32_e32 v22, 3, v8
	v_readlane_b32 s16, v253, 48
	s_lshl_b64 s[4:5], s[96:97], 1
	v_readlane_b32 s26, v253, 58
	v_readlane_b32 s27, v253, 59
	s_add_u32 s4, s26, s4
	s_addc_u32 s5, s27, s5
	v_readlane_b32 s17, v253, 49
	v_readlane_b32 s18, v253, 50
	v_readlane_b32 s19, v253, 51
	v_readlane_b32 s20, v253, 52
	v_readlane_b32 s21, v253, 53
	v_readlane_b32 s22, v253, 54
	v_readlane_b32 s23, v253, 55
	v_readlane_b32 s24, v253, 56
	v_readlane_b32 s25, v253, 57
	v_readlane_b32 s28, v253, 60
	v_readlane_b32 s29, v253, 61
	v_readlane_b32 s30, v253, 62
	v_readlane_b32 s31, v253, 63
	s_waitcnt vmcnt(0)
	ds_write2_b32 v7, v0, v1 offset1:1
	ds_write2_b32 v7, v2, v3 offset0:2 offset1:3
	v_add_u32_e32 v0, 16, v6
	v_ashrrev_i32_e32 v1, 31, v0
	v_lshlrev_b64 v[0:1], 12, v[0:1]
	v_lshl_add_u64 v[0:1], v[4:5], 0, v[0:1]
	v_mov_b32_e32 v0, v240
	v_mov_b32_e32 v1, v241
	v_mov_b32_e32 v2, v242
	v_mov_b32_e32 v3, v243
	s_waitcnt vmcnt(0)
	ds_write2_b32 v9, v0, v1 offset1:1
	v_add_u32_e32 v0, 0x1048, v7
	ds_write2_b32 v0, v2, v3 offset1:1
	v_add_u32_e32 v0, 32, v6
	v_ashrrev_i32_e32 v1, 31, v0
	v_lshlrev_b64 v[0:1], 12, v[0:1]
	v_lshl_add_u64 v[0:1], v[4:5], 0, v[0:1]
	v_mov_b32_e32 v0, v244
	v_mov_b32_e32 v1, v245
	v_mov_b32_e32 v2, v246
	v_mov_b32_e32 v3, v247
	v_add_u32_e32 v9, 0x2080, v7
	s_waitcnt vmcnt(0)
	ds_write2_b32 v9, v0, v1 offset1:1
	v_add_u32_e32 v0, 0x2088, v7
	ds_write2_b32 v0, v2, v3 offset1:1
	v_add_u32_e32 v0, 48, v6
	v_ashrrev_i32_e32 v1, 31, v0
	v_lshlrev_b64 v[0:1], 12, v[0:1]
	v_lshl_add_u64 v[0:1], v[4:5], 0, v[0:1]
	v_mov_b32_e32 v0, v248
	v_mov_b32_e32 v1, v249
	v_mov_b32_e32 v2, v250
	v_mov_b32_e32 v3, v251
	v_add_u32_e32 v4, 0x30c0, v7
	s_waitcnt vmcnt(0)
	ds_write2_b32 v4, v0, v1 offset1:1
	v_add_u32_e32 v0, 0x30c8, v7
	ds_write2_b32 v0, v2, v3 offset1:1
	v_lshlrev_b32_e32 v0, 3, v8
	v_and_b32_e32 v2, 56, v0
	v_lshlrev_b32_e32 v188, 1, v2
	v_mul_u32_u24_e32 v2, 0x104, v2
	v_lshl_add_u32 v2, v22, 2, v2
	s_waitcnt lgkmcnt(0)
	s_barrier
	ds_read2_b32 v[6:7], v2 offset1:32
	ds_read2_b32 v[8:9], v2 offset0:65 offset1:97
	ds_read2_b32 v[10:11], v2 offset0:130 offset1:162
	ds_read2_b32 v[12:13], v2 offset0:195 offset1:227
	v_add_u32_e32 v2, 0x400, v2
	ds_read2_b32 v[14:15], v2 offset0:4 offset1:36
	ds_read2_b32 v[16:17], v2 offset0:69 offset1:101
	ds_read2_b32 v[18:19], v2 offset0:134 offset1:166
	ds_read2_b32 v[20:21], v2 offset0:199 offset1:231
	v_add_u32_e32 v22, s2, v22
	v_ashrrev_i32_e32 v23, 31, v22
	v_lshl_add_u64 v[0:1], s[4:5], 0, v[188:189]
	v_lshlrev_b64 v[24:25], 13, v[22:23]
	s_waitcnt lgkmcnt(6)
	v_cvt_pk_bf16_f32 v2, v6, v8
	s_waitcnt lgkmcnt(4)
	v_cvt_pk_bf16_f32 v3, v10, v12
	s_waitcnt lgkmcnt(2)
	v_cvt_pk_bf16_f32 v4, v14, v16
	s_waitcnt lgkmcnt(0)
	v_cvt_pk_bf16_f32 v5, v18, v20
	v_lshl_add_u64 v[24:25], v[0:1], 0, v[24:25]
	v_add_u32_e32 v6, 32, v22
	global_store_dwordx4 v[24:25], v[2:5], off
	s_nop 1
	v_cvt_pk_bf16_f32 v2, v7, v9
	v_ashrrev_i32_e32 v7, 31, v6
	v_lshlrev_b64 v[6:7], 13, v[6:7]
	v_cvt_pk_bf16_f32 v3, v11, v13
	v_cvt_pk_bf16_f32 v4, v15, v17
	v_cvt_pk_bf16_f32 v5, v19, v21
	v_lshl_add_u64 v[0:1], v[0:1], 0, v[6:7]
	global_store_dwordx4 v[0:1], v[2:5], off

; template <bool MAP = false>
; DI void conv_tile(const float* __restrict__ src, int N, int K, bfu* __restrict__ dst, const float* __restrict__ g,
;                   int tk, int tn, char* smem, int ldk = -1) {
;     ...
;   for (int j = 0; j < 4; ++j) {
;     int k = (tid >> 4) + 16 * j, n4 = (tid & 15) * 4;
;     int gn = tn * 64 + n4, gk = tk * 64 + k;
;     float4 v = make_float4(0.f, 0.f, 0.f, 0.f);
;     const int og = MAP ? in_colmap(gn) : (gn < N ? gn : -1);
;     if (og >= 0) v = *(const float4*)(src + (size_t)gk * N + og);
;     float gg = g ? g[gk] : 1.f;
;     T[k * 65 + n4 + 0] = v.x * gg; T[k * 65 + n4 + 1] = v.y * gg; T[k * 65 + n4 + 2] = v.z * gg; T[k * 65 + n4 + 3] = v.w * gg;
;   }
.LBB0_1938:
	s_movk_i32 s4, 0x104
	v_lshlrev_b32_e32 v9, 2, v13
	v_mul_lo_u32 v8, v8, s4
	s_waitcnt vmcnt(0)
	v_pk_mul_f32 v[0:1], v[0:1], v[12:13] op_sel_hi:[1,0]
	v_add_u32_e32 v13, v9, v8
	ds_write2_b32 v13, v0, v1 offset1:1
	v_pk_mul_f32 v[0:1], v[2:3], v[12:13] op_sel_hi:[1,0]
	ds_write2_b32 v13, v0, v1 offset0:2 offset1:3
	v_add_u32_e32 v0, 16, v6
	v_ashrrev_i32_e32 v1, 31, v0
	v_lshlrev_b64 v[0:1], 14, v[0:1]
	v_lshl_add_u64 v[0:1], v[4:5], 0, v[0:1]
	v_mov_b32_e32 v0, v240
	v_mov_b32_e32 v1, v241
	v_mov_b32_e32 v2, v242
	v_mov_b32_e32 v3, v243
	s_and_b64 vcc, exec, s[2:3]
	v_lshl_add_u64 v[8:9], v[6:7], 2, s[94:95]
	s_cbranch_vccnz .LBB0_1940
	global_load_dword v10, v[8:9], off offset:64

; DI int TID() { int t = threadIdx.x; asm volatile("" : "+v"(t)); return t; }
; DI unsigned pk2(float a, float b) { f32x2_t v = {a, b}; bf16x2_t r_ = __builtin_convertvector(v, bf16x2_t); return __builtin_bit_cast(unsigned, r_); }
; template <bool MAP = false>
; DI void conv_tile(const float* __restrict__ src, int N, int K, bfu* __restrict__ dst, const float* __restrict__ g,
;                   int tk, int tn, char* smem, int ldk = -1) {
;     ...
;   float* T = (float*)smem;
;   const int tid = TID();
;   __syncthreads();
; #pragma unroll
;   for (int j = 0; j < 4; ++j) {
;     int k = (tid >> 4) + 16 * j, n4 = (tid & 15) * 4;
;     int gn = tn * 64 + n4, gk = tk * 64 + k;
;     float4 v = make_float4(0.f, 0.f, 0.f, 0.f);
;     const int og = MAP ? in_colmap(gn) : (gn < N ? gn : -1);
;     if (og >= 0) v = *(const float4*)(src + (size_t)gk * N + og);
;     float gg = g ? g[gk] : 1.f;
;     T[k * 65 + n4 + 0] = v.x * gg; T[k * 65 + n4 + 1] = v.y * gg; T[k * 65 + n4 + 2] = v.z * gg; T[k * 65 + n4 + 3] = v.w * gg;
;   }
;   __syncthreads();
; #pragma unroll
;   for (int j = 0; j < 2; ++j) {
;     int n = (tid >> 3) + 32 * j, kc = tid & 7;
;     float e[8];
; #pragma unroll
;     for (int q = 0; q < 8; ++q) e[q] = T[(kc * 8 + q) * 65 + n];
;     u32x4 o = {pk2(e[0], e[1]), pk2(e[2], e[3]), pk2(e[4], e[5]), pk2(e[6], e[7])};
;     *(u32x4*)(dst + (size_t)(tn * 64 + n) * LK + tk * 64 + kc * 8) = o;
;   }
.LBB0_1946:
	s_andn2_b64 vcc, exec, s[2:3]
	s_cbranch_vccnz .LBB0_1948
	v_mov_b32_e32 v8, v224
	s_lshl_b32 s3, s12, 2
	s_lshl_b32 s2, s12, 6
	v_lshlrev_b32_e32 v0, 2, v8
	s_and_b32 s3, s3, 0x7c0
	v_ashrrev_i32_e32 v2, 4, v8
	v_and_b32_e32 v3, 60, v0
	s_and_b32 s2, s2, 0x3c0
	s_add_i32 s96, s3, 0xfffffc00
	v_or_b32_e32 v0, s2, v3
	v_add_u32_e32 v6, s96, v2
	v_lshlrev_b32_e32 v188, 2, v0
	v_ashrrev_i32_e32 v7, 31, v6
	v_lshl_add_u64 v[4:5], s[52:53], 0, v[188:189]
	v_lshlrev_b64 v[0:1], 12, v[6:7]
	s_movk_i32 s3, 0x104
	v_lshl_add_u64 v[0:1], v[4:5], 0, v[0:1]
	v_mul_lo_u32 v2, v2, s3
	s_waitcnt vmcnt(63) expcnt(7) lgkmcnt(15)
	s_barrier
	v_lshl_add_u32 v7, v3, 2, v2
	v_add_u32_e32 v210, 16, v6
	v_ashrrev_i32_e32 v211, 31, v210
	v_lshlrev_b64 v[210:211], 12, v[210:211]
	v_lshl_add_u64 v[210:211], v[4:5], 0, v[210:211]
	global_load_dwordx4 v[240:243], v[210:211], off
	v_add_u32_e32 v210, 32, v6
	v_ashrrev_i32_e32 v211, 31, v210
	v_lshlrev_b64 v[210:211], 12, v[210:211]
	v_lshl_add_u64 v[210:211], v[4:5], 0, v[210:211]
	global_load_dwordx4 v[244:247], v[210:211], off
	v_add_u32_e32 v210, 48, v6
	v_ashrrev_i32_e32 v211, 31, v210
	v_lshlrev_b64 v[210:211], 12, v[210:211]
	v_lshl_add_u64 v[210:211], v[4:5], 0, v[210:211]
	global_load_dwordx4 v[248:251], v[210:211], off
	global_load_dwordx4 v[0:3], v[0:1], off
	v_add_u32_e32 v9, 0x1040, v7
	v_ashrrev_i32_e32 v22, 3, v8
	v_readlane_b32 s16, v253, 48
	s_lshl_b64 s[4:5], s[96:97], 1
	v_readlane_b32 s22, v253, 54
	v_readlane_b32 s23, v253, 55
	s_add_u32 s4, s22, s4
	s_addc_u32 s5, s23, s5
	v_readlane_b32 s17, v253, 49
	v_readlane_b32 s18, v253, 50
	v_readlane_b32 s19, v253, 51
	v_readlane_b32 s20, v253, 52
	v_readlane_b32 s21, v253, 53
	v_readlane_b32 s24, v253, 56
	v_readlane_b32 s25, v253, 57
	v_readlane_b32 s26, v253, 58
	v_readlane_b32 s27, v253, 59
	v_readlane_b32 s28, v253, 60
	v_readlane_b32 s29, v253, 61
	v_readlane_b32 s30, v253, 62
	v_readlane_b32 s31, v253, 63
	s_waitcnt vmcnt(0)
	ds_write2_b32 v7, v0, v1 offset1:1
	ds_write2_b32 v7, v2, v3 offset0:2 offset1:3
	v_add_u32_e32 v0, 16, v6
	v_ashrrev_i32_e32 v1, 31, v0
	v_lshlrev_b64 v[0:1], 12, v[0:1]
	v_lshl_add_u64 v[0:1], v[4:5], 0, v[0:1]
	v_mov_b32_e32 v0, v240
	v_mov_b32_e32 v1, v241
	v_mov_b32_e32 v2, v242
	v_mov_b32_e32 v3, v243
	s_waitcnt vmcnt(0)
	ds_write2_b32 v9, v0, v1 offset1:1
	v_add_u32_e32 v0, 0x1048, v7
	ds_write2_b32 v0, v2, v3 offset1:1
	v_add_u32_e32 v0, 32, v6
	v_ashrrev_i32_e32 v1, 31, v0
	v_lshlrev_b64 v[0:1], 12, v[0:1]
	v_lshl_add_u64 v[0:1], v[4:5], 0, v[0:1]
	v_mov_b32_e32 v0, v244
	v_mov_b32_e32 v1, v245
	v_mov_b32_e32 v2, v246
	v_mov_b32_e32 v3, v247
	v_add_u32_e32 v9, 0x2080, v7
	s_waitcnt vmcnt(0)
	ds_write2_b32 v9, v0, v1 offset1:1
	v_add_u32_e32 v0, 0x2088, v7
	ds_write2_b32 v0, v2, v3 offset1:1
	v_add_u32_e32 v0, 48, v6
	v_ashrrev_i32_e32 v1, 31, v0
	v_lshlrev_b64 v[0:1], 12, v[0:1]
	v_lshl_add_u64 v[0:1], v[4:5], 0, v[0:1]
	v_mov_b32_e32 v0, v248
	v_mov_b32_e32 v1, v249
	v_mov_b32_e32 v2, v250
	v_mov_b32_e32 v3, v251
	v_add_u32_e32 v4, 0x30c0, v7
	s_waitcnt vmcnt(0)
	ds_write2_b32 v4, v0, v1 offset1:1
	v_add_u32_e32 v0, 0x30c8, v7
	ds_write2_b32 v0, v2, v3 offset1:1
	v_lshlrev_b32_e32 v0, 3, v8
	v_and_b32_e32 v2, 56, v0
	v_lshlrev_b32_e32 v188, 1, v2
	v_mul_u32_u24_e32 v2, 0x104, v2
	v_lshl_add_u32 v2, v22, 2, v2
	s_waitcnt lgkmcnt(0)
	s_barrier
	ds_read2_b32 v[6:7], v2 offset1:32
	ds_read2_b32 v[8:9], v2 offset0:65 offset1:97
	ds_read2_b32 v[10:11], v2 offset0:130 offset1:162
	ds_read2_b32 v[12:13], v2 offset0:195 offset1:227
	v_add_u32_e32 v2, 0x400, v2
	ds_read2_b32 v[14:15], v2 offset0:4 offset1:36
	ds_read2_b32 v[16:17], v2 offset0:69 offset1:101
	ds_read2_b32 v[18:19], v2 offset0:134 offset1:166
	ds_read2_b32 v[20:21], v2 offset0:199 offset1:231
	v_add_u32_e32 v22, s2, v22
	v_ashrrev_i32_e32 v23, 31, v22
	v_lshl_add_u64 v[0:1], s[4:5], 0, v[188:189]
	v_lshlrev_b64 v[24:25], 11, v[22:23]
	s_waitcnt lgkmcnt(6)
	v_cvt_pk_bf16_f32 v2, v6, v8
	s_waitcnt lgkmcnt(4)
	v_cvt_pk_bf16_f32 v3, v10, v12
	s_waitcnt lgkmcnt(2)
	v_cvt_pk_bf16_f32 v4, v14, v16
	s_waitcnt lgkmcnt(0)
	v_cvt_pk_bf16_f32 v5, v18, v20
	v_lshl_add_u64 v[24:25], v[0:1], 0, v[24:25]
	v_add_u32_e32 v6, 32, v22
	global_store_dwordx4 v[24:25], v[2:5], off
	s_nop 1
	v_cvt_pk_bf16_f32 v2, v7, v9
	v_ashrrev_i32_e32 v7, 31, v6
	v_lshlrev_b64 v[6:7], 11, v[6:7]
	v_cvt_pk_bf16_f32 v3, v11, v13
	v_cvt_pk_bf16_f32 v4, v15, v17
	v_cvt_pk_bf16_f32 v5, v19, v21
	v_lshl_add_u64 v[0:1], v[0:1], 0, v[6:7]
	global_store_dwordx4 v[0:1], v[2:5], off

; DI int TID() { int t = threadIdx.x; asm volatile("" : "+v"(t)); return t; }
; DI unsigned pk2(float a, float b) { f32x2_t v = {a, b}; bf16x2_t r_ = __builtin_convertvector(v, bf16x2_t); return __builtin_bit_cast(unsigned, r_); }
; template <bool MAP = false>
; DI void conv_tile(const float* __restrict__ src, int N, int K, bfu* __restrict__ dst, const float* __restrict__ g,
;                   int tk, int tn, char* smem, int ldk = -1) {
;     ...
;   float* T = (float*)smem;
;   const int tid = TID();
;   __syncthreads();
; #pragma unroll
;   for (int j = 0; j < 4; ++j) {
;     int k = (tid >> 4) + 16 * j, n4 = (tid & 15) * 4;
;     int gn = tn * 64 + n4, gk = tk * 64 + k;
;     float4 v = make_float4(0.f, 0.f, 0.f, 0.f);
;     const int og = MAP ? in_colmap(gn) : (gn < N ? gn : -1);
;     if (og >= 0) v = *(const float4*)(src + (size_t)gk * N + og);
;     float gg = g ? g[gk] : 1.f;
;     T[k * 65 + n4 + 0] = v.x * gg; T[k * 65 + n4 + 1] = v.y * gg; T[k * 65 + n4 + 2] = v.z * gg; T[k * 65 + n4 + 3] = v.w * gg;
;   }
;   __syncthreads();
; #pragma unroll
;   for (int j = 0; j < 2; ++j) {
;     int n = (tid >> 3) + 32 * j, kc = tid & 7;
;     float e[8];
; #pragma unroll
;     for (int q = 0; q < 8; ++q) e[q] = T[(kc * 8 + q) * 65 + n];
;     u32x4 o = {pk2(e[0], e[1]), pk2(e[2], e[3]), pk2(e[4], e[5]), pk2(e[6], e[7])};
;     *(u32x4*)(dst + (size_t)(tn * 64 + n) * LK + tk * 64 + kc * 8) = o;
;   }
; DI void conv_item_C(const Params& p, int L, int it, char* smem) {
;   if (it < 256) { int t = it; int n = t >> 6; t &= 63; conv_tile(p.w_branch + ((size_t)L * 4 + n) * 256 * D, D, 256, p.wt_br + (size_t)n * 256, nullptr, t / 16, t % 16, smem, 1024); }
.LBB0_1949:
	s_andn2_b64 vcc, exec, s[2:3]
	s_cbranch_vccnz .LBB0_1951
	s_lshr_b32 s96, s12, 6
	s_lshl_b64 s[2:3], s[96:97], 20
	s_add_u32 s4, s89, s2
	v_readlane_b32 s2, v255, 31
	v_readlane_b32 s16, v253, 48
	s_addc_u32 s5, s2, s3
	s_lshl_b64 s[2:3], s[96:97], 9
	v_readlane_b32 s20, v253, 52
	v_readlane_b32 s21, v253, 53
	s_add_u32 s20, s20, s2
	v_mov_b32_e32 v8, v224
	s_addc_u32 s3, s21, s3
	s_lshl_b32 s2, s12, 6
	v_lshlrev_b32_e32 v0, 2, v8
	s_lshl_b32 s12, s12, 2
	v_ashrrev_i32_e32 v2, 4, v8
	v_and_b32_e32 v3, 60, v0
	s_and_b32 s2, s2, 0x3c0
	s_and_b32 s12, s12, 0xc0
	v_or_b32_e32 v0, s2, v3
	v_add_u32_e32 v6, s12, v2
	v_lshlrev_b32_e32 v188, 2, v0
	v_ashrrev_i32_e32 v7, 31, v6
	v_lshl_add_u64 v[4:5], s[4:5], 0, v[188:189]
	v_lshlrev_b64 v[0:1], 12, v[6:7]
	s_movk_i32 s4, 0x104
	v_lshl_add_u64 v[0:1], v[4:5], 0, v[0:1]
	v_mul_lo_u32 v2, v2, s4
	s_waitcnt vmcnt(63) expcnt(7) lgkmcnt(15)
	s_barrier
	v_lshl_add_u32 v7, v3, 2, v2
	v_add_u32_e32 v210, 16, v6
	v_ashrrev_i32_e32 v211, 31, v210
	v_lshlrev_b64 v[210:211], 12, v[210:211]
	v_lshl_add_u64 v[210:211], v[4:5], 0, v[210:211]
	global_load_dwordx4 v[240:243], v[210:211], off
	v_add_u32_e32 v210, 32, v6
	v_ashrrev_i32_e32 v211, 31, v210
	v_lshlrev_b64 v[210:211], 12, v[210:211]
	v_lshl_add_u64 v[210:211], v[4:5], 0, v[210:211]
	global_load_dwordx4 v[244:247], v[210:211], off
	v_add_u32_e32 v210, 48, v6
	v_ashrrev_i32_e32 v211, 31, v210
	v_lshlrev_b64 v[210:211], 12, v[210:211]
	v_lshl_add_u64 v[210:211], v[4:5], 0, v[210:211]
	global_load_dwordx4 v[248:251], v[210:211], off
	global_load_dwordx4 v[0:3], v[0:1], off
	v_add_u32_e32 v9, 0x1040, v7
	v_ashrrev_i32_e32 v22, 3, v8
	s_lshl_b32 s4, s12, 1
	s_add_u32 s4, s20, s4
	s_addc_u32 s5, s3, 0
	v_readlane_b32 s17, v253, 49
	v_readlane_b32 s18, v253, 50
	v_readlane_b32 s19, v253, 51
	v_readlane_b32 s22, v253, 54
	v_readlane_b32 s23, v253, 55
	v_readlane_b32 s24, v253, 56
	v_readlane_b32 s25, v253, 57
	v_readlane_b32 s26, v253, 58
	v_readlane_b32 s27, v253, 59
	v_readlane_b32 s28, v253, 60
	v_readlane_b32 s29, v253, 61
	v_readlane_b32 s30, v253, 62
	v_readlane_b32 s31, v253, 63
	s_waitcnt vmcnt(0)
	ds_write2_b32 v7, v0, v1 offset1:1
	ds_write2_b32 v7, v2, v3 offset0:2 offset1:3
	v_add_u32_e32 v0, 16, v6
	v_ashrrev_i32_e32 v1, 31, v0
	v_lshlrev_b64 v[0:1], 12, v[0:1]
	v_lshl_add_u64 v[0:1], v[4:5], 0, v[0:1]
	v_mov_b32_e32 v0, v240
	v_mov_b32_e32 v1, v241
	v_mov_b32_e32 v2, v242
	v_mov_b32_e32 v3, v243
	s_waitcnt vmcnt(0)
	ds_write2_b32 v9, v0, v1 offset1:1
	v_add_u32_e32 v0, 0x1048, v7
	ds_write2_b32 v0, v2, v3 offset1:1
	v_add_u32_e32 v0, 32, v6
	v_ashrrev_i32_e32 v1, 31, v0
	v_lshlrev_b64 v[0:1], 12, v[0:1]
	v_lshl_add_u64 v[0:1], v[4:5], 0, v[0:1]
	v_mov_b32_e32 v0, v244
	v_mov_b32_e32 v1, v245
	v_mov_b32_e32 v2, v246
	v_mov_b32_e32 v3, v247
	v_add_u32_e32 v9, 0x2080, v7
	s_waitcnt vmcnt(0)
	ds_write2_b32 v9, v0, v1 offset1:1
	v_add_u32_e32 v0, 0x2088, v7
	ds_write2_b32 v0, v2, v3 offset1:1
	v_add_u32_e32 v0, 48, v6
	v_ashrrev_i32_e32 v1, 31, v0
	v_lshlrev_b64 v[0:1], 12, v[0:1]
	v_lshl_add_u64 v[0:1], v[4:5], 0, v[0:1]
	v_mov_b32_e32 v0, v248
	v_mov_b32_e32 v1, v249
	v_mov_b32_e32 v2, v250
	v_mov_b32_e32 v3, v251
	v_add_u32_e32 v4, 0x30c0, v7
	s_waitcnt vmcnt(0)
	ds_write2_b32 v4, v0, v1 offset1:1
	v_add_u32_e32 v0, 0x30c8, v7
	ds_write2_b32 v0, v2, v3 offset1:1
	v_lshlrev_b32_e32 v0, 3, v8
	v_and_b32_e32 v2, 56, v0
	v_lshlrev_b32_e32 v188, 1, v2
	v_mul_u32_u24_e32 v2, 0x104, v2
	v_lshl_add_u32 v2, v22, 2, v2
	s_waitcnt lgkmcnt(0)
	s_barrier
	ds_read2_b32 v[6:7], v2 offset1:32
	ds_read2_b32 v[8:9], v2 offset0:65 offset1:97
	ds_read2_b32 v[10:11], v2 offset0:130 offset1:162
	ds_read2_b32 v[12:13], v2 offset0:195 offset1:227
	v_add_u32_e32 v2, 0x400, v2
	ds_read2_b32 v[14:15], v2 offset0:4 offset1:36
	ds_read2_b32 v[16:17], v2 offset0:69 offset1:101
	ds_read2_b32 v[18:19], v2 offset0:134 offset1:166
	ds_read2_b32 v[20:21], v2 offset0:199 offset1:231
	v_add_u32_e32 v22, s2, v22
	v_ashrrev_i32_e32 v23, 31, v22
	v_lshl_add_u64 v[0:1], s[4:5], 0, v[188:189]
	v_lshlrev_b64 v[24:25], 11, v[22:23]
	s_waitcnt lgkmcnt(6)
	v_cvt_pk_bf16_f32 v2, v6, v8
	s_waitcnt lgkmcnt(4)
	v_cvt_pk_bf16_f32 v3, v10, v12
	s_waitcnt lgkmcnt(2)
	v_cvt_pk_bf16_f32 v4, v14, v16
	s_waitcnt lgkmcnt(0)
	v_cvt_pk_bf16_f32 v5, v18, v20
	v_lshl_add_u64 v[24:25], v[0:1], 0, v[24:25]
	v_add_u32_e32 v6, 32, v22
	global_store_dwordx4 v[24:25], v[2:5], off
	s_nop 1
	v_cvt_pk_bf16_f32 v2, v7, v9
	v_ashrrev_i32_e32 v7, 31, v6
	v_lshlrev_b64 v[6:7], 11, v[6:7]
	v_cvt_pk_bf16_f32 v3, v11, v13
	v_cvt_pk_bf16_f32 v4, v15, v17
	v_cvt_pk_bf16_f32 v5, v19, v21
	v_lshl_add_u64 v[0:1], v[0:1], 0, v[6:7]
	global_store_dwordx4 v[0:1], v[2:5], off

; template <bool MAP = false>
; DI void conv_tile(const float* __restrict__ src, int N, int K, bfu* __restrict__ dst, const float* __restrict__ g,
;                   int tk, int tn, char* smem, int ldk = -1) {
;     ...
;   for (int j = 0; j < 4; ++j) {
;     int k = (tid >> 4) + 16 * j, n4 = (tid & 15) * 4;
;     int gn = tn * 64 + n4, gk = tk * 64 + k;
;     float4 v = make_float4(0.f, 0.f, 0.f, 0.f);
;     const int og = MAP ? in_colmap(gn) : (gn < N ? gn : -1);
;     if (og >= 0) v = *(const float4*)(src + (size_t)gk * N + og);
;     float gg = g ? g[gk] : 1.f;
;     T[k * 65 + n4 + 0] = v.x * gg; T[k * 65 + n4 + 1] = v.y * gg; T[k * 65 + n4 + 2] = v.z * gg; T[k * 65 + n4 + 3] = v.w * gg;
;   }
.LBB0_1974:
	s_movk_i32 s16, 0x104
	v_lshlrev_b32_e32 v9, 2, v14
	s_waitcnt vmcnt(0)
	v_pk_mul_f32 v[0:1], v[0:1], v[12:13] op_sel_hi:[1,0]
	v_mul_lo_u32 v13, v13, s16
	v_add_u32_e32 v9, v9, v13
	ds_write2_b32 v9, v0, v1 offset1:1
	v_pk_mul_f32 v[0:1], v[2:3], v[12:13] op_sel_hi:[1,0]
	ds_write2_b32 v9, v0, v1 offset0:2 offset1:3
	v_add_u32_e32 v0, 16, v8
	v_ashrrev_i32_e32 v1, 31, v0
	v_lshlrev_b64 v[0:1], 11, v[0:1]
	v_lshl_add_u64 v[0:1], v[6:7], 0, v[0:1]
	v_mov_b32_e32 v0, v240
	v_mov_b32_e32 v1, v241
	v_mov_b32_e32 v2, v242
	v_mov_b32_e32 v3, v243
	s_and_b64 vcc, exec, s[2:3]
	s_cbranch_vccnz .LBB0_1976
	global_load_dword v10, v[4:5], off offset:64

; template <bool MAP = false>
; DI void conv_tile(const float* __restrict__ src, int N, int K, bfu* __restrict__ dst, const float* __restrict__ g,
;                   int tk, int tn, char* smem, int ldk = -1) {
;     ...
;   for (int j = 0; j < 4; ++j) {
;     int k = (tid >> 4) + 16 * j, n4 = (tid & 15) * 4;
;     int gn = tn * 64 + n4, gk = tk * 64 + k;
;     float4 v = make_float4(0.f, 0.f, 0.f, 0.f);
;     const int og = MAP ? in_colmap(gn) : (gn < N ? gn : -1);
;     if (og >= 0) v = *(const float4*)(src + (size_t)gk * N + og);
;     float gg = g ? g[gk] : 1.f;
;     T[k * 65 + n4 + 0] = v.x * gg; T[k * 65 + n4 + 1] = v.y * gg; T[k * 65 + n4 + 2] = v.z * gg; T[k * 65 + n4 + 3] = v.w * gg;
;   }
.LBB0_1999:
	s_movk_i32 s16, 0x104
	v_lshlrev_b32_e32 v5, 2, v5
	v_mul_lo_u32 v7, v4, s16
	s_waitcnt vmcnt(0)
	v_pk_mul_f32 v[0:1], v[0:1], v[8:9] op_sel_hi:[1,0]
	v_add_u32_e32 v7, v5, v7
	ds_write2_b32 v7, v0, v1 offset1:1
	v_pk_mul_f32 v[0:1], v[2:3], v[8:9] op_sel_hi:[1,0]
	ds_write2_b32 v7, v0, v1 offset0:2 offset1:3
	v_mov_b32_e32 v0, 0
	v_mov_b32_e32 v1, 0
	v_mov_b32_e32 v2, 0
	v_mov_b32_e32 v3, 0
	s_and_saveexec_b64 vcc, s[2:3]
	s_cbranch_execz .LBB0_2001
	v_add_u32_e32 v2, 16, v6
	v_mov_b64_e32 v[0:1], s[34:35]
	s_movk_i32 s16, 0x6ac0
	v_mad_i64_i32 v[0:1], s[84:85], v2, s16, v[0:1]
	v_lshl_add_u64 v[0:1], v[188:189], 2, v[0:1]
	v_mov_b32_e32 v0, v240
	v_mov_b32_e32 v1, v241
	v_mov_b32_e32 v2, v242
	v_mov_b32_e32 v3, v243

; template <bool MAP = false>
; DI void conv_tile(const float* __restrict__ src, int N, int K, bfu* __restrict__ dst, const float* __restrict__ g,
;                   int tk, int tn, char* smem, int ldk = -1) {
;     ...
;   for (int j = 0; j < 4; ++j) {
;     int k = (tid >> 4) + 16 * j, n4 = (tid & 15) * 4;
;     int gn = tn * 64 + n4, gk = tk * 64 + k;
;     float4 v = make_float4(0.f, 0.f, 0.f, 0.f);
;     const int og = MAP ? in_colmap(gn) : (gn < N ? gn : -1);
;     if (og >= 0) v = *(const float4*)(src + (size_t)gk * N + og);
;     float gg = g ? g[gk] : 1.f;
;     T[k * 65 + n4 + 0] = v.x * gg; T[k * 65 + n4 + 1] = v.y * gg; T[k * 65 + n4 + 2] = v.z * gg; T[k * 65 + n4 + 3] = v.w * gg;
;   }
.LBB0_2004:
	s_waitcnt vmcnt(0)
	v_pk_mul_f32 v[0:1], v[0:1], v[8:9] op_sel_hi:[1,0]
	v_add_u32_e32 v10, 0x1040, v7
	ds_write2_b32 v10, v0, v1 offset1:1
	v_pk_mul_f32 v[0:1], v[2:3], v[8:9] op_sel_hi:[1,0]
	v_add_u32_e32 v2, 0x1048, v7
	ds_write2_b32 v2, v0, v1 offset1:1
	v_mov_b32_e32 v0, 0
	v_mov_b32_e32 v1, 0
	v_mov_b32_e32 v2, 0
	v_mov_b32_e32 v3, 0
	s_and_saveexec_b64 vcc, s[2:3]
	s_cbranch_execz .LBB0_2006
	v_add_u32_e32 v2, 32, v6
	v_mov_b64_e32 v[0:1], s[34:35]
	s_movk_i32 s16, 0x6ac0
	v_mad_i64_i32 v[0:1], s[84:85], v2, s16, v[0:1]
	v_lshl_add_u64 v[0:1], v[188:189], 2, v[0:1]
	v_mov_b32_e32 v0, v244
	v_mov_b32_e32 v1, v245
	v_mov_b32_e32 v2, v246
	v_mov_b32_e32 v3, v247

; template <bool MAP = false>
; DI void conv_tile(const float* __restrict__ src, int N, int K, bfu* __restrict__ dst, const float* __restrict__ g,
;                   int tk, int tn, char* smem, int ldk = -1) {
;     ...
;   for (int j = 0; j < 4; ++j) {
;     int k = (tid >> 4) + 16 * j, n4 = (tid & 15) * 4;
;     int gn = tn * 64 + n4, gk = tk * 64 + k;
;     float4 v = make_float4(0.f, 0.f, 0.f, 0.f);
;     const int og = MAP ? in_colmap(gn) : (gn < N ? gn : -1);
;     if (og >= 0) v = *(const float4*)(src + (size_t)gk * N + og);
;     float gg = g ? g[gk] : 1.f;
;     T[k * 65 + n4 + 0] = v.x * gg; T[k * 65 + n4 + 1] = v.y * gg; T[k * 65 + n4 + 2] = v.z * gg; T[k * 65 + n4 + 3] = v.w * gg;
;   }
.LBB0_2009:
	s_waitcnt vmcnt(0)
	v_pk_mul_f32 v[0:1], v[0:1], v[8:9] op_sel_hi:[1,0]
	v_add_u32_e32 v10, 0x2080, v7
	ds_write2_b32 v10, v0, v1 offset1:1
	v_pk_mul_f32 v[0:1], v[2:3], v[8:9] op_sel_hi:[1,0]
	v_add_u32_e32 v2, 0x2088, v7
	s_mov_b64 s[54:55], 0x1000
	ds_write2_b32 v2, v0, v1 offset1:1
	v_mov_b32_e32 v0, 0
	v_mov_b32_e32 v1, 0
	v_mov_b32_e32 v2, 0
	v_mov_b32_e32 v3, 0
	s_and_saveexec_b64 s[4:5], s[2:3]
	s_cbranch_execz .LBB0_2011
	v_add_u32_e32 v2, 48, v6
	v_mov_b64_e32 v[0:1], s[34:35]
	s_movk_i32 s2, 0x6ac0
	v_mad_i64_i32 v[0:1], s[2:3], v2, s2, v[0:1]
	v_lshl_add_u64 v[0:1], v[188:189], 2, v[0:1]
	v_mov_b32_e32 v0, v248
	v_mov_b32_e32 v1, v249
	v_mov_b32_e32 v2, v250
	v_mov_b32_e32 v3, v251
